# FFN-up x2 and W_in: next-tile scalar scheduling block moved from the tile head into two load segments of the peeled first K iteration
# baseline (speedup 1.0000x reference)
; #define PG8_STAGE(bufoff, gbase, voff) do { _Pragma("unroll") for (int _i = 0; _i < 2; ++_i) \
;         __builtin_amdgcn_global_load_lds((const unsigned*)((const char*)(gbase) + (voff)[_i]), (LAS unsigned*)(lds + (bufoff) + ldsw + _i * 8192), 16, 0, 0); } while (0)
; #define PG8_LDA(dst, b, h) do { _Pragma("unroll") for (int m = 0; m < 4; ++m) _Pragma("unroll") for (int k = 0; k < 2; ++k) dst[m][k] = *(const LAS bf16x8*)(lds + PG8_SA(b, h) + aoff + m * 2048 + k * 1024); } while (0)
; #define PG8_WAIT_V(n) asm volatile("s_waitcnt vmcnt(" #n ")" ::: "memory")
; #define PG8_WAIT_L(n) asm volatile("s_waitcnt lgkmcnt(" #n ")" ::: "memory")
;     DI bool next(int i, Unit& u) const {
;         const long L = (long)i * G + c; if (L >= total) return false;
;         u.g = (int)(L / nwg); int wgid = (int)(L % nwg);
;         { const int q = nwg / NXCD, r = nwg % NXCD, xcd = wgid % NXCD, off = wgid / NXCD; wgid = (xcd < r ? xcd * (q + 1) : r * (q + 1) + (xcd - r) * q) + off; }
;         const int nig = WGM * nN, gid = wgid / nig, fm = gid * WGM, gsz = (nM - fm) < WGM ? (nM - fm) : WGM;
;         u.pm = fm + ((wgid % nig) % gsz); u.pn = (wgid % nig) / gsz; return true;
;     }
; template <class Epi>
; DI void gemm_phase(LAS unsigned char* lds, const int wid, const Gemm g, const Order& S, const Epi& E) {
;     ...
;         const bool has_next = S.next(ui + 1, nxt);
;         const char* nA = has_next ? (const char*)(g.A + (size_t)nxt.g * g.gsA + (size_t)nxt.pm * BM * g.lda) : cA;
;         const char* nB = has_next ? (const char*)(g.Bt + (size_t)nxt.g * g.gsB + (size_t)nxt.pn * BM * g.ldb) : cB;
;         for (int t = 0; t < nt; t += 2) {
;             const bool last = (t == nt - 2);
;             const char* a1 = cA + (size_t)(t + 1) * kstep;
;             const char* a2 = last ? nA : cA + (size_t)(t + 2) * kstep; const char* b2 = last ? nB : cB + (size_t)(t + 2) * kstep;
;             const char* a3 = a2 + kstep; const char* b3 = b2 + kstep;
;             PG8_LDB(B0, 0, 0); PG8_LDB(B1, 0, 1); PG8_SCHED; PG8_LDA(At, 0, 0); PG8_STAGE(PG8_SA(1, 1), a1 + hstepA, voffA);
;             PG8_WAIT_V(8); PG8_WAIT_L(0); PG8_BAR; PG8_MMA(0, 0, At, B0); PG8_MMA(0, 1, At, B1); PG8_BAR; PG8_SCHED;
;             PG8_LDA(At, 0, 1); PG8_STAGE(PG8_SB(0, 0), b2, voffB); PG8_STAGE(PG8_SB(0, 1), b2 + hstepB, voffB); PG8_STAGE(PG8_SA(0, 0), a2, voffA);
.LBB0_225:
.LBB0_227:
	s_add_u32 s42, s42, 0x40080
	s_addc_u32 s43, s43, 0
	s_add_u32 s61, s44, 0x100
	v_mov_b32_e32 v0, 0
	s_addc_u32 s62, s45, 0
	s_mov_b32 s63, -2
	ds_read_b128 v[164:167], v151
	ds_read_b128 v[168:171], v151 offset:1024
	ds_read_b128 v[172:175], v151 offset:2048
	ds_read_b128 v[176:179], v151 offset:3072
	ds_read_b128 v[180:183], v155
	ds_read_b128 v[184:187], v155 offset:1024
	ds_read_b128 v[188:191], v155 offset:2048
	ds_read_b128 v[192:195], v155 offset:3072
	s_add_u32 s44, s42, 0xfffc0080
	s_addc_u32 s45, s43, -1
	s_cmp_eq_u32 s63, 12
	s_cselect_b32 s47, s31, s45
	s_cselect_b32 s46, s59, s44
	s_cselect_b32 s45, s35, s62
	s_cselect_b32 s44, s60, s61
	v_lshl_add_u64 v[144:145], s[42:43], 0, v[136:137]
	s_add_i32 m0, s27, 0xc000
	ds_read_b128 v[196:199], v159
	ds_read_b128 v[200:203], v159 offset:1024
	ds_read_b128 v[204:207], v159 offset:2048
	ds_read_b128 v[208:211], v159 offset:3072
	ds_read_b128 v[216:219], v159 offset:4096
	ds_read_b128 v[220:223], v159 offset:5120
	ds_read_b128 v[224:227], v159 offset:6144
	ds_read_b128 v[228:231], v159 offset:7168
	global_load_lds_dwordx4 v[144:145], off
	v_lshl_add_u64 v[144:145], s[42:43], 0, v[138:139]
	s_add_i32 m0, s27, 0xe000
	s_nop 0
	global_load_lds_dwordx4 v[144:145], off
	s_waitcnt vmcnt(8)
	s_waitcnt lgkmcnt(0)
	s_barrier
	s_setprio 1
	s_waitcnt lgkmcnt(0)
	v_mfma_f32_16x16x32_bf16 v[124:127], v[164:167], v[196:199], 0
	v_mfma_f32_16x16x32_bf16 v[120:123], v[172:175], v[196:199], 0
	v_mfma_f32_16x16x32_bf16 v[108:111], v[164:167], v[204:207], 0
	v_mfma_f32_16x16x32_bf16 v[104:107], v[172:175], v[204:207], 0
	v_mfma_f32_16x16x32_bf16 v[92:95], v[164:167], v[216:219], 0
	v_mfma_f32_16x16x32_bf16 v[88:91], v[172:175], v[216:219], 0
	v_mfma_f32_16x16x32_bf16 v[76:79], v[164:167], v[224:227], 0
	v_mfma_f32_16x16x32_bf16 v[72:75], v[172:175], v[224:227], 0
	v_mfma_f32_16x16x32_bf16 v[124:127], v[168:171], v[200:203], v[124:127]
	v_mfma_f32_16x16x32_bf16 v[120:123], v[176:179], v[200:203], v[120:123]
	v_mfma_f32_16x16x32_bf16 v[108:111], v[168:171], v[208:211], v[108:111]
	v_mfma_f32_16x16x32_bf16 v[104:107], v[176:179], v[208:211], v[104:107]
	v_mfma_f32_16x16x32_bf16 v[92:95], v[168:171], v[220:223], v[92:95]
	v_mfma_f32_16x16x32_bf16 v[88:91], v[176:179], v[220:223], v[88:91]
	v_mfma_f32_16x16x32_bf16 v[76:79], v[168:171], v[228:231], v[76:79]
	v_mfma_f32_16x16x32_bf16 v[72:75], v[176:179], v[228:231], v[72:75]
	s_setprio 0
	s_setprio 1
	v_mfma_f32_16x16x32_bf16 v[116:119], v[180:183], v[196:199], 0
	v_mfma_f32_16x16x32_bf16 v[112:115], v[188:191], v[196:199], 0
	v_mfma_f32_16x16x32_bf16 v[100:103], v[180:183], v[204:207], 0
	v_mfma_f32_16x16x32_bf16 v[96:99], v[188:191], v[204:207], 0
	v_mfma_f32_16x16x32_bf16 v[84:87], v[180:183], v[216:219], 0
	v_mfma_f32_16x16x32_bf16 v[80:83], v[188:191], v[216:219], 0
	v_mfma_f32_16x16x32_bf16 v[68:71], v[180:183], v[224:227], 0
	v_mfma_f32_16x16x32_bf16 v[64:67], v[188:191], v[224:227], 0
	v_mfma_f32_16x16x32_bf16 v[116:119], v[184:187], v[200:203], v[116:119]
	v_mfma_f32_16x16x32_bf16 v[112:115], v[192:195], v[200:203], v[112:115]
	v_mfma_f32_16x16x32_bf16 v[100:103], v[184:187], v[208:211], v[100:103]
	v_mfma_f32_16x16x32_bf16 v[96:99], v[192:195], v[208:211], v[96:99]
	v_mfma_f32_16x16x32_bf16 v[84:87], v[184:187], v[220:223], v[84:87]
	v_mfma_f32_16x16x32_bf16 v[80:83], v[192:195], v[220:223], v[80:83]
	v_mfma_f32_16x16x32_bf16 v[68:71], v[184:187], v[228:231], v[68:71]
	v_mfma_f32_16x16x32_bf16 v[64:67], v[192:195], v[228:231], v[64:67]
	s_setprio 0
	s_barrier
	s_add_i32 s64, s56, s94
	v_lshl_add_u64 v[144:145], s[44:45], 0, v[132:133]
	s_mov_b32 m0, s64
	ds_read_b128 v[196:199], v159 offset:16384
	ds_read_b128 v[200:203], v159 offset:17408
	ds_read_b128 v[204:207], v159 offset:18432
	ds_read_b128 v[208:211], v159 offset:19456
	ds_read_b128 v[216:219], v159 offset:20480
	ds_read_b128 v[220:223], v159 offset:21504
	ds_read_b128 v[224:227], v159 offset:22528
	ds_read_b128 v[228:231], v159 offset:23552
	global_load_lds_dwordx4 v[144:145], off
	s_add_i32 m0, s64, 0x2000
	s_add_u32 s64, s44, 0x40000
	v_lshl_add_u64 v[148:149], s[44:45], 0, v[128:129]
	s_addc_u32 s65, s45, 0
	s_add_i32 s66, s57, s94
	global_load_lds_dwordx4 v[148:149], off
	v_lshl_add_u64 v[152:153], s[64:65], 0, v[132:133]
	s_mov_b32 m0, s66
	v_lshl_add_u64 v[156:157], s[46:47], 0, v[130:131]
	global_load_lds_dwordx4 v[152:153], off
	v_lshl_add_u64 v[152:153], s[64:65], 0, v[128:129]
	s_add_i32 m0, s66, 0x2000
	s_nop 0
	global_load_lds_dwordx4 v[152:153], off
	v_lshl_add_u64 v[152:153], s[46:47], 0, v[134:135]
	s_mov_b32 m0, s27
	s_nop 0
	global_load_lds_dwordx4 v[152:153], off
	s_mov_b32 m0, s41
	s_nop 0
	global_load_lds_dwordx4 v[156:157], off
	s_add_i32 s50, s50, 1
	s_mul_i32 s6, s50, s53
	s_mul_hi_u32 s7, s50, s54
	s_add_i32 s7, s7, s6
	s_mul_i32 s6, s50, s54
	s_add_u32 s36, s6, s2
	s_addc_u32 s37, s7, s3
	v_cmp_lt_i64_e64 s[6:7], s[36:37], v[140:141]
	s_mul_i32 s35, s37, 0xba2e8ba3
	s_mul_hi_u32 s38, s36, 0xba2e8ba3
	s_mul_hi_u32 s34, s37, 0xba2e8ba3
	s_add_u32 s35, s35, s38
	s_mul_i32 s31, s36, 0x2e8ba2e8
	s_addc_u32 s34, s34, 0
	s_mul_hi_u32 s30, s36, 0x2e8ba2e8
	s_add_u32 s31, s31, s35
	s_addc_u32 s30, s30, 0
	s_add_u32 s30, s34, s30
	s_addc_u32 s31, 0, 0
	s_mul_i32 s35, s37, 0x2e8ba2e8
	s_mul_hi_u32 s34, s37, 0x2e8ba2e8
	s_add_u32 s30, s35, s30
	s_addc_u32 s31, s34, s31
	s_ashr_i32 s34, s37, 31
	s_mul_i32 s35, s34, 0x2e8ba2e8
	s_mul_hi_u32 s37, s34, 0xba2e8ba3
	s_add_i32 s35, s37, s35
	s_mul_i32 s34, s34, 0xba2e8ba3
	s_add_i32 s35, s35, s34
	s_add_u32 s30, s30, s34
	s_addc_u32 s31, s31, s35
	s_ashr_i64 s[34:35], s[30:31], 10
	s_lshr_b32 s30, s31, 31
	s_add_u32 s30, s34, s30
	s_mulk_i32 s30, 0x1600
	s_sub_i32 s30, s36, s30
	s_sext_i32_i16 s31, s30
	s_bfe_u32 s31, s31, 0x3001c
	s_add_i32 s31, s30, s31
	s_waitcnt vmcnt(8)
	s_waitcnt lgkmcnt(0)
	s_barrier
; #define PG8_STAGE(bufoff, gbase, voff) do { _Pragma("unroll") for (int _i = 0; _i < 2; ++_i) \
;         __builtin_amdgcn_global_load_lds((const unsigned*)((const char*)(gbase) + (voff)[_i]), (LAS unsigned*)(lds + (bufoff) + ldsw + _i * 8192), 16, 0, 0); } while (0)
; #define PG8_LDA(dst, b, h) do { _Pragma("unroll") for (int m = 0; m < 4; ++m) _Pragma("unroll") for (int k = 0; k < 2; ++k) dst[m][k] = *(const LAS bf16x8*)(lds + PG8_SA(b, h) + aoff + m * 2048 + k * 1024); } while (0)
; #define PG8_LDB(dst, b, h) do { _Pragma("unroll") for (int n = 0; n < 2; ++n) _Pragma("unroll") for (int k = 0; k < 2; ++k) dst[n][k] = *(const LAS bf16x8*)(lds + PG8_SB(b, h) + boff + n * 2048 + k * 1024); } while (0)
; #define PG8_MMA(ai, bj, At, Bt) do { __builtin_amdgcn_s_setprio(1); _Pragma("unroll") for (int m = 0; m < 4; ++m) _Pragma("unroll") for (int n = 0; n < 2; ++n) _Pragma("unroll") for (int k = 0; k < 2; ++k) \
;         acc[ai][bj][m][n] = __builtin_amdgcn_mfma_f32_16x16x32_bf16(Bt[n][k], At[m][k], acc[ai][bj][m][n], 0, 0, 0); __builtin_amdgcn_s_setprio(0); } while (0)
; #define PG8_WAIT_V(n) asm volatile("s_waitcnt vmcnt(" #n ")" ::: "memory")
; #define PG8_WAIT_L(n) asm volatile("s_waitcnt lgkmcnt(" #n ")" ::: "memory")
; #define PG8_BAR __builtin_amdgcn_s_barrier()
; #define PG8_SCHED __builtin_amdgcn_sched_barrier(0)
;     DI bool next(int i, Unit& u) const {
;     ...
;         { const int q = nwg / NXCD, r = nwg % NXCD, xcd = wgid % NXCD, off = wgid / NXCD; wgid = (xcd < r ? xcd * (q + 1) : r * (q + 1) + (xcd - r) * q) + off; }
;         const int nig = WGM * nN, gid = wgid / nig, fm = gid * WGM, gsz = (nM - fm) < WGM ? (nM - fm) : WGM;
;         u.pm = fm + ((wgid % nig) % gsz); u.pn = (wgid % nig) / gsz; return true;
;     }
; template <class Epi>
; DI void gemm_phase(LAS unsigned char* lds, const int wid, const Gemm g, const Order& S, const Epi& E) {
;     ...
;             PG8_WAIT_V(8); PG8_WAIT_L(0); PG8_BAR; PG8_MMA(1, 0, At, B0); PG8_MMA(1, 1, At, B1); PG8_BAR; PG8_SCHED;
;             PG8_LDB(B0, 1, 0); PG8_LDB(B1, 1, 1); PG8_SCHED; PG8_LDA(At, 1, 0); PG8_STAGE(PG8_SA(0, 1), a2 + hstepA, voffA);
	s_setprio 1
	s_waitcnt lgkmcnt(0)
	v_mfma_f32_16x16x32_bf16 v[60:63], v[164:167], v[196:199], 0
	v_mfma_f32_16x16x32_bf16 v[56:59], v[172:175], v[196:199], 0
	v_mfma_f32_16x16x32_bf16 v[44:47], v[164:167], v[204:207], 0
	v_mfma_f32_16x16x32_bf16 v[40:43], v[172:175], v[204:207], 0
	v_mfma_f32_16x16x32_bf16 v[28:31], v[164:167], v[216:219], 0
	v_mfma_f32_16x16x32_bf16 v[24:27], v[172:175], v[216:219], 0
	v_mfma_f32_16x16x32_bf16 v[12:15], v[164:167], v[224:227], 0
	v_mfma_f32_16x16x32_bf16 v[8:11], v[172:175], v[224:227], 0
	v_mfma_f32_16x16x32_bf16 v[60:63], v[168:171], v[200:203], v[60:63]
	v_mfma_f32_16x16x32_bf16 v[56:59], v[176:179], v[200:203], v[56:59]
	v_mfma_f32_16x16x32_bf16 v[44:47], v[168:171], v[208:211], v[44:47]
	v_mfma_f32_16x16x32_bf16 v[40:43], v[176:179], v[208:211], v[40:43]
	v_mfma_f32_16x16x32_bf16 v[28:31], v[168:171], v[220:223], v[28:31]
	v_mfma_f32_16x16x32_bf16 v[24:27], v[176:179], v[220:223], v[24:27]
	v_mfma_f32_16x16x32_bf16 v[12:15], v[168:171], v[228:231], v[12:15]
	v_mfma_f32_16x16x32_bf16 v[8:11], v[176:179], v[228:231], v[8:11]
	s_setprio 0
	s_setprio 1
	v_mfma_f32_16x16x32_bf16 v[52:55], v[180:183], v[196:199], 0
	v_mfma_f32_16x16x32_bf16 v[48:51], v[188:191], v[196:199], 0
	v_mfma_f32_16x16x32_bf16 v[36:39], v[180:183], v[204:207], 0
	v_mfma_f32_16x16x32_bf16 v[32:35], v[188:191], v[204:207], 0
	v_mfma_f32_16x16x32_bf16 v[20:23], v[180:183], v[216:219], 0
	v_mfma_f32_16x16x32_bf16 v[16:19], v[188:191], v[216:219], 0
	v_mfma_f32_16x16x32_bf16 v[4:7], v[180:183], v[224:227], 0
	v_mfma_f32_16x16x32_bf16 v[0:3], v[188:191], v[224:227], 0
	v_mfma_f32_16x16x32_bf16 v[52:55], v[184:187], v[200:203], v[52:55]
	v_mfma_f32_16x16x32_bf16 v[48:51], v[192:195], v[200:203], v[48:51]
	v_mfma_f32_16x16x32_bf16 v[36:39], v[184:187], v[208:211], v[36:39]
	v_mfma_f32_16x16x32_bf16 v[32:35], v[192:195], v[208:211], v[32:35]
	v_mfma_f32_16x16x32_bf16 v[20:23], v[184:187], v[220:223], v[20:23]
	v_mfma_f32_16x16x32_bf16 v[16:19], v[192:195], v[220:223], v[16:19]
	v_mfma_f32_16x16x32_bf16 v[4:7], v[184:187], v[228:231], v[4:7]
	v_mfma_f32_16x16x32_bf16 v[0:3], v[192:195], v[228:231], v[0:3]
	s_setprio 0
	s_barrier
	s_add_i32 s64, 0, 0x18000
	v_add_u32_e32 v146, s64, v147
	s_add_i32 s65, 0, 0x1c000
	ds_read_b128 v[164:167], v146
	ds_read_b128 v[168:171], v146 offset:1024
	ds_read_b128 v[172:175], v146 offset:2048
	ds_read_b128 v[176:179], v146 offset:3072
	v_add_u32_e32 v146, s65, v147
	ds_read_b128 v[180:183], v146
	ds_read_b128 v[184:187], v146 offset:1024
	ds_read_b128 v[188:191], v146 offset:2048
	ds_read_b128 v[192:195], v146 offset:3072
	s_add_u32 s46, s46, 0x40000
	s_addc_u32 s47, s47, 0
	s_mov_b32 m0, s48
	v_lshl_add_u64 v[160:161], s[46:47], 0, v[134:135]
	ds_read_b128 v[196:199], v159 offset:32768
	ds_read_b128 v[200:203], v159 offset:33792
	ds_read_b128 v[204:207], v159 offset:34816
	ds_read_b128 v[208:211], v159 offset:35840
	ds_read_b128 v[216:219], v159 offset:36864
	ds_read_b128 v[220:223], v159 offset:37888
	ds_read_b128 v[224:227], v159 offset:38912
	ds_read_b128 v[228:231], v159 offset:39936
	global_load_lds_dwordx4 v[160:161], off
	v_lshl_add_u64 v[160:161], s[46:47], 0, v[130:131]
	s_mov_b32 m0, s49
	s_nop 0
	global_load_lds_dwordx4 v[160:161], off
	s_sext_i32_i16 s34, s31
	s_and_b32 s31, s31, 0xfff8
	s_sub_i32 s30, s30, s31
	s_ashr_i32 s34, s34, 3
	s_sext_i32_i16 s31, s30
	s_cmp_lt_i32 s31, 0
	s_cselect_b32 s31, s26, 0x2c0
	s_mul_i32 s30, s30, s31
	s_add_i32 s30, s30, s34
	s_sext_i32_i16 s31, s30
	s_mulk_i32 s31, 0xba3
	s_lshr_b32 s34, s31, 31
	s_ashr_i32 s31, s31, 19
	s_add_i32 s31, s31, s34
	s_lshl_b32 s34, s31, 3
	s_mulk_i32 s31, 0xb0
	s_sub_i32 s30, s30, s31
	s_sext_i32_i16 s31, s30
	s_bfe_u32 s31, s31, 0x3001c
	s_add_i32 s31, s30, s31
	s_sext_i32_i16 s35, s31
	s_and_b32 s31, s31, 0xfff8
	s_sub_i32 s30, s30, s31
	s_sext_i32_i16 s30, s30
	s_add_i32 s30, s34, s30
	s_ashr_i32 s34, s35, 3
	s_ashr_i32 s31, s30, 31
	s_lshl_b64 s[36:37], s[30:31], 19
	s_add_u32 s36, s21, s36
	s_addc_u32 s37, s25, s37
	s_and_b64 s[38:39], s[6:7], exec
	s_cselect_b32 s31, s37, s43
	s_cselect_b32 s59, s36, s42
	s_ashr_i32 s35, s34, 31
	s_lshl_b64 s[38:39], s[34:35], 19
	s_add_u32 s38, s8, s38
	s_addc_u32 s39, s9, s39
	s_and_b64 vcc, s[6:7], exec
	s_cselect_b32 s35, s39, s45
	s_cselect_b32 s60, s38, s44
	s_waitcnt vmcnt(8)
	s_waitcnt lgkmcnt(0)
	s_barrier
; #define PG8_STAGE(bufoff, gbase, voff) do { _Pragma("unroll") for (int _i = 0; _i < 2; ++_i) \
;         __builtin_amdgcn_global_load_lds((const unsigned*)((const char*)(gbase) + (voff)[_i]), (LAS unsigned*)(lds + (bufoff) + ldsw + _i * 8192), 16, 0, 0); } while (0)
; #define PG8_LDA(dst, b, h) do { _Pragma("unroll") for (int m = 0; m < 4; ++m) _Pragma("unroll") for (int k = 0; k < 2; ++k) dst[m][k] = *(const LAS bf16x8*)(lds + PG8_SA(b, h) + aoff + m * 2048 + k * 1024); } while (0)
; #define PG8_MMA(ai, bj, At, Bt) do { __builtin_amdgcn_s_setprio(1); _Pragma("unroll") for (int m = 0; m < 4; ++m) _Pragma("unroll") for (int n = 0; n < 2; ++n) _Pragma("unroll") for (int k = 0; k < 2; ++k) \
;         acc[ai][bj][m][n] = __builtin_amdgcn_mfma_f32_16x16x32_bf16(Bt[n][k], At[m][k], acc[ai][bj][m][n], 0, 0, 0); __builtin_amdgcn_s_setprio(0); } while (0)
; #define PG8_WAIT_V(n) asm volatile("s_waitcnt vmcnt(" #n ")" ::: "memory")
; #define PG8_WAIT_L(n) asm volatile("s_waitcnt lgkmcnt(" #n ")" ::: "memory")
; #define PG8_BAR __builtin_amdgcn_s_barrier()
; #define PG8_SCHED __builtin_amdgcn_sched_barrier(0)
; template <class Epi>
; DI void gemm_phase(LAS unsigned char* lds, const int wid, const Gemm g, const Order& S, const Epi& E) {
;     ...
;             PG8_WAIT_V(8); PG8_WAIT_L(0); PG8_BAR; PG8_MMA(0, 0, At, B0); PG8_MMA(0, 1, At, B1); PG8_BAR; PG8_SCHED;
;             PG8_LDA(At, 1, 1); PG8_STAGE(PG8_SB(1, 0), b3, voffB); PG8_STAGE(PG8_SB(1, 1), b3 + hstepB, voffB); PG8_STAGE(PG8_SA(1, 0), a3, voffA);
;             PG8_WAIT_V(8); PG8_WAIT_L(0); PG8_BAR; PG8_MMA(1, 0, At, B0); PG8_MMA(1, 1, At, B1); PG8_BAR; PG8_SCHED;
	s_setprio 1
	s_waitcnt lgkmcnt(0)
	v_mfma_f32_16x16x32_bf16 v[124:127], v[164:167], v[196:199], v[124:127]
	v_mfma_f32_16x16x32_bf16 v[120:123], v[172:175], v[196:199], v[120:123]
	v_mfma_f32_16x16x32_bf16 v[108:111], v[164:167], v[204:207], v[108:111]
	v_mfma_f32_16x16x32_bf16 v[104:107], v[172:175], v[204:207], v[104:107]
	v_mfma_f32_16x16x32_bf16 v[92:95], v[164:167], v[216:219], v[92:95]
	v_mfma_f32_16x16x32_bf16 v[88:91], v[172:175], v[216:219], v[88:91]
	v_mfma_f32_16x16x32_bf16 v[76:79], v[164:167], v[224:227], v[76:79]
	v_mfma_f32_16x16x32_bf16 v[72:75], v[172:175], v[224:227], v[72:75]
	v_mfma_f32_16x16x32_bf16 v[124:127], v[168:171], v[200:203], v[124:127]
	v_mfma_f32_16x16x32_bf16 v[120:123], v[176:179], v[200:203], v[120:123]
	v_mfma_f32_16x16x32_bf16 v[108:111], v[168:171], v[208:211], v[108:111]
	v_mfma_f32_16x16x32_bf16 v[104:107], v[176:179], v[208:211], v[104:107]
	v_mfma_f32_16x16x32_bf16 v[92:95], v[168:171], v[220:223], v[92:95]
	v_mfma_f32_16x16x32_bf16 v[88:91], v[176:179], v[220:223], v[88:91]
	v_mfma_f32_16x16x32_bf16 v[76:79], v[168:171], v[228:231], v[76:79]
	v_mfma_f32_16x16x32_bf16 v[72:75], v[176:179], v[228:231], v[72:75]
	s_setprio 0
	s_setprio 1
	v_mfma_f32_16x16x32_bf16 v[116:119], v[180:183], v[196:199], v[116:119]
	v_mfma_f32_16x16x32_bf16 v[112:115], v[188:191], v[196:199], v[112:115]
	v_mfma_f32_16x16x32_bf16 v[100:103], v[180:183], v[204:207], v[100:103]
	v_mfma_f32_16x16x32_bf16 v[96:99], v[188:191], v[204:207], v[96:99]
	v_mfma_f32_16x16x32_bf16 v[84:87], v[180:183], v[216:219], v[84:87]
	v_mfma_f32_16x16x32_bf16 v[80:83], v[188:191], v[216:219], v[80:83]
	v_mfma_f32_16x16x32_bf16 v[68:71], v[180:183], v[224:227], v[68:71]
	v_mfma_f32_16x16x32_bf16 v[64:67], v[188:191], v[224:227], v[64:67]
	v_mfma_f32_16x16x32_bf16 v[116:119], v[184:187], v[200:203], v[116:119]
	v_mfma_f32_16x16x32_bf16 v[112:115], v[192:195], v[200:203], v[112:115]
	v_mfma_f32_16x16x32_bf16 v[100:103], v[184:187], v[208:211], v[100:103]
	v_mfma_f32_16x16x32_bf16 v[96:99], v[192:195], v[208:211], v[96:99]
	v_mfma_f32_16x16x32_bf16 v[84:87], v[184:187], v[220:223], v[84:87]
	v_mfma_f32_16x16x32_bf16 v[80:83], v[192:195], v[220:223], v[80:83]
	v_mfma_f32_16x16x32_bf16 v[68:71], v[184:187], v[228:231], v[68:71]
	v_mfma_f32_16x16x32_bf16 v[64:67], v[192:195], v[228:231], v[64:67]
	s_setprio 0
	s_barrier
	s_add_i32 s46, s64, s94
	v_lshl_add_u64 v[144:145], v[144:145], 0, s[16:17]
	s_mov_b32 m0, s46
	ds_read_b128 v[196:199], v159 offset:49152
	ds_read_b128 v[200:203], v159 offset:50176
	ds_read_b128 v[204:207], v159 offset:51200
	ds_read_b128 v[208:211], v159 offset:52224
	ds_read_b128 v[216:219], v159 offset:53248
	ds_read_b128 v[220:223], v159 offset:54272
	ds_read_b128 v[224:227], v159 offset:55296
	ds_read_b128 v[228:231], v159 offset:56320
	global_load_lds_dwordx4 v[144:145], off
	s_add_i32 m0, s46, 0x2000
	s_add_u32 s44, s44, 0x40080
	v_lshl_add_u64 v[144:145], v[148:149], 0, s[16:17]
	s_addc_u32 s45, s45, 0
	s_add_i32 s46, s65, s94
	global_load_lds_dwordx4 v[144:145], off
	v_lshl_add_u64 v[144:145], s[44:45], 0, v[132:133]
	s_mov_b32 m0, s46
	s_nop 0
	global_load_lds_dwordx4 v[144:145], off
	v_lshl_add_u64 v[144:145], s[44:45], 0, v[128:129]
	s_add_i32 m0, s46, 0x2000
	s_nop 0
	global_load_lds_dwordx4 v[144:145], off
	v_lshl_add_u64 v[144:145], v[152:153], 0, s[16:17]
	s_mov_b32 m0, s51
	s_nop 0
	global_load_lds_dwordx4 v[144:145], off
	v_lshl_add_u64 v[144:145], v[156:157], 0, s[16:17]
	s_mov_b32 m0, s52
	s_nop 0
	global_load_lds_dwordx4 v[144:145], off
	s_waitcnt vmcnt(8)
	s_waitcnt lgkmcnt(0)
	s_barrier
	s_setprio 1
	s_waitcnt lgkmcnt(0)
	v_mfma_f32_16x16x32_bf16 v[60:63], v[164:167], v[196:199], v[60:63]
	v_mfma_f32_16x16x32_bf16 v[56:59], v[172:175], v[196:199], v[56:59]
	v_mfma_f32_16x16x32_bf16 v[44:47], v[164:167], v[204:207], v[44:47]
	v_mfma_f32_16x16x32_bf16 v[40:43], v[172:175], v[204:207], v[40:43]
	v_mfma_f32_16x16x32_bf16 v[28:31], v[164:167], v[216:219], v[28:31]
	v_mfma_f32_16x16x32_bf16 v[24:27], v[172:175], v[216:219], v[24:27]
	v_mfma_f32_16x16x32_bf16 v[12:15], v[164:167], v[224:227], v[12:15]
	v_mfma_f32_16x16x32_bf16 v[8:11], v[172:175], v[224:227], v[8:11]
	v_mfma_f32_16x16x32_bf16 v[60:63], v[168:171], v[200:203], v[60:63]
	v_mfma_f32_16x16x32_bf16 v[56:59], v[176:179], v[200:203], v[56:59]
	v_mfma_f32_16x16x32_bf16 v[44:47], v[168:171], v[208:211], v[44:47]
	v_mfma_f32_16x16x32_bf16 v[40:43], v[176:179], v[208:211], v[40:43]
	v_mfma_f32_16x16x32_bf16 v[28:31], v[168:171], v[220:223], v[28:31]
	v_mfma_f32_16x16x32_bf16 v[24:27], v[176:179], v[220:223], v[24:27]
	v_mfma_f32_16x16x32_bf16 v[12:15], v[168:171], v[228:231], v[12:15]
	v_mfma_f32_16x16x32_bf16 v[8:11], v[176:179], v[228:231], v[8:11]
	s_setprio 0
	s_setprio 1
	v_mfma_f32_16x16x32_bf16 v[52:55], v[180:183], v[196:199], v[52:55]
	v_mfma_f32_16x16x32_bf16 v[48:51], v[188:191], v[196:199], v[48:51]
	v_mfma_f32_16x16x32_bf16 v[36:39], v[180:183], v[204:207], v[36:39]
	v_mfma_f32_16x16x32_bf16 v[32:35], v[188:191], v[204:207], v[32:35]
	v_mfma_f32_16x16x32_bf16 v[20:23], v[180:183], v[216:219], v[20:23]
	v_mfma_f32_16x16x32_bf16 v[16:19], v[188:191], v[216:219], v[16:19]
	v_mfma_f32_16x16x32_bf16 v[4:7], v[180:183], v[224:227], v[4:7]
	v_mfma_f32_16x16x32_bf16 v[0:3], v[188:191], v[224:227], v[0:3]
	v_mfma_f32_16x16x32_bf16 v[52:55], v[184:187], v[200:203], v[52:55]
	v_mfma_f32_16x16x32_bf16 v[48:51], v[192:195], v[200:203], v[48:51]
	v_mfma_f32_16x16x32_bf16 v[36:39], v[184:187], v[208:211], v[36:39]
	v_mfma_f32_16x16x32_bf16 v[32:35], v[192:195], v[208:211], v[32:35]
	v_mfma_f32_16x16x32_bf16 v[20:23], v[184:187], v[220:223], v[20:23]
	v_mfma_f32_16x16x32_bf16 v[16:19], v[192:195], v[220:223], v[16:19]
	v_mfma_f32_16x16x32_bf16 v[4:7], v[184:187], v[228:231], v[4:7]
	v_mfma_f32_16x16x32_bf16 v[0:3], v[192:195], v[228:231], v[0:3]
	s_setprio 0
	s_barrier
	s_add_i32 s63, s63, 2
	s_add_u32 s42, s42, 0x100
	s_addc_u32 s43, s43, 0
	s_add_u32 s61, s61, 0x100
	s_addc_u32 s62, s62, 0
	s_cmp_gt_u32 s63, 13
	s_cbranch_scc0 .LBB0_228
	s_branch .Lpeel_exit_0

; #define PG8_STAGE(bufoff, gbase, voff) do { _Pragma("unroll") for (int _i = 0; _i < 2; ++_i) \
;         __builtin_amdgcn_global_load_lds((const unsigned*)((const char*)(gbase) + (voff)[_i]), (LAS unsigned*)(lds + (bufoff) + ldsw + _i * 8192), 16, 0, 0); } while (0)
; #define PG8_LDA(dst, b, h) do { _Pragma("unroll") for (int m = 0; m < 4; ++m) _Pragma("unroll") for (int k = 0; k < 2; ++k) dst[m][k] = *(const LAS bf16x8*)(lds + PG8_SA(b, h) + aoff + m * 2048 + k * 1024); } while (0)
; #define PG8_WAIT_V(n) asm volatile("s_waitcnt vmcnt(" #n ")" ::: "memory")
; #define PG8_WAIT_L(n) asm volatile("s_waitcnt lgkmcnt(" #n ")" ::: "memory")
;     DI bool next(int i, Unit& u) const {
;         const long L = (long)i * G + c; if (L >= total) return false;
;         u.g = (int)(L / nwg); int wgid = (int)(L % nwg);
;         { const int q = nwg / NXCD, r = nwg % NXCD, xcd = wgid % NXCD, off = wgid / NXCD; wgid = (xcd < r ? xcd * (q + 1) : r * (q + 1) + (xcd - r) * q) + off; }
;         const int nig = WGM * nN, gid = wgid / nig, fm = gid * WGM, gsz = (nM - fm) < WGM ? (nM - fm) : WGM;
;         u.pm = fm + ((wgid % nig) % gsz); u.pn = (wgid % nig) / gsz; return true;
;     }
; template <class Epi>
; DI void gemm_phase(LAS unsigned char* lds, const int wid, const Gemm g, const Order& S, const Epi& E) {
;     ...
;         const bool has_next = S.next(ui + 1, nxt);
;         const char* nA = has_next ? (const char*)(g.A + (size_t)nxt.g * g.gsA + (size_t)nxt.pm * BM * g.lda) : cA;
;         const char* nB = has_next ? (const char*)(g.Bt + (size_t)nxt.g * g.gsB + (size_t)nxt.pn * BM * g.ldb) : cB;
;         for (int t = 0; t < nt; t += 2) {
;             const bool last = (t == nt - 2);
;             const char* a1 = cA + (size_t)(t + 1) * kstep;
;             const char* a2 = last ? nA : cA + (size_t)(t + 2) * kstep; const char* b2 = last ? nB : cB + (size_t)(t + 2) * kstep;
;             const char* a3 = a2 + kstep; const char* b3 = b2 + kstep;
;             PG8_LDB(B0, 0, 0); PG8_LDB(B1, 0, 1); PG8_SCHED; PG8_LDA(At, 0, 0); PG8_STAGE(PG8_SA(1, 1), a1 + hstepA, voffA);
;             PG8_WAIT_V(8); PG8_WAIT_L(0); PG8_BAR; PG8_MMA(0, 0, At, B0); PG8_MMA(0, 1, At, B1); PG8_BAR; PG8_SCHED;
;             PG8_LDA(At, 0, 1); PG8_STAGE(PG8_SB(0, 0), b2, voffB); PG8_STAGE(PG8_SB(0, 1), b2 + hstepB, voffB); PG8_STAGE(PG8_SA(0, 0), a2, voffA);
.LBB0_397:
.LBB0_399:
	s_add_u32 s12, s12, 0x40080
	s_addc_u32 s13, s13, 0
	s_add_u32 s68, s64, 0x100
	v_mov_b32_e32 v0, 0
	s_addc_u32 s69, s65, 0
	s_mov_b32 s70, -2
	s_waitcnt lgkmcnt(0)
	ds_read_b128 v[146:149], v163
	ds_read_b128 v[150:153], v163 offset:1024
	ds_read_b128 v[154:157], v163 offset:2048
	ds_read_b128 v[158:161], v163 offset:3072
	ds_read_b128 v[168:171], v164
	ds_read_b128 v[172:175], v164 offset:1024
	ds_read_b128 v[176:179], v164 offset:2048
	ds_read_b128 v[180:183], v164 offset:3072
	s_add_u32 s64, s12, 0xfffc0080
	s_addc_u32 s65, s13, -1
	s_cmp_eq_u32 s70, 12
	s_cselect_b32 s67, s11, s65
	s_cselect_b32 s66, s16, s64
	s_cselect_b32 s65, s57, s69
	s_cselect_b32 s64, s59, s68
	v_lshl_add_u64 v[212:213], s[12:13], 0, v[138:139]
	s_add_i32 m0, s6, 0xc000
	ds_read_b128 v[184:187], v165
	ds_read_b128 v[188:191], v165 offset:1024
	ds_read_b128 v[192:195], v165 offset:2048
	ds_read_b128 v[196:199], v165 offset:3072
	ds_read_b128 v[200:203], v165 offset:4096
	ds_read_b128 v[204:207], v165 offset:5120
	ds_read_b128 v[208:211], v165 offset:6144
	ds_read_b128 v[216:219], v165 offset:7168
	global_load_lds_dwordx4 v[212:213], off
	v_lshl_add_u64 v[212:213], s[12:13], 0, v[140:141]
	s_add_i32 m0, s6, 0xe000
	s_nop 0
	global_load_lds_dwordx4 v[212:213], off
	s_waitcnt vmcnt(8)
	s_waitcnt lgkmcnt(0)
	s_barrier
	s_setprio 1
	s_waitcnt lgkmcnt(0)
	v_mfma_f32_16x16x32_bf16 v[124:127], v[146:149], v[184:187], 0
	v_mfma_f32_16x16x32_bf16 v[120:123], v[154:157], v[184:187], 0
	v_mfma_f32_16x16x32_bf16 v[108:111], v[146:149], v[192:195], 0
	v_mfma_f32_16x16x32_bf16 v[104:107], v[154:157], v[192:195], 0
	v_mfma_f32_16x16x32_bf16 v[92:95], v[146:149], v[200:203], 0
	v_mfma_f32_16x16x32_bf16 v[88:91], v[154:157], v[200:203], 0
	v_mfma_f32_16x16x32_bf16 v[76:79], v[146:149], v[208:211], 0
	v_mfma_f32_16x16x32_bf16 v[72:75], v[154:157], v[208:211], 0
	v_mfma_f32_16x16x32_bf16 v[124:127], v[150:153], v[188:191], v[124:127]
	v_mfma_f32_16x16x32_bf16 v[120:123], v[158:161], v[188:191], v[120:123]
	v_mfma_f32_16x16x32_bf16 v[108:111], v[150:153], v[196:199], v[108:111]
	v_mfma_f32_16x16x32_bf16 v[104:107], v[158:161], v[196:199], v[104:107]
	v_mfma_f32_16x16x32_bf16 v[92:95], v[150:153], v[204:207], v[92:95]
	v_mfma_f32_16x16x32_bf16 v[88:91], v[158:161], v[204:207], v[88:91]
	v_mfma_f32_16x16x32_bf16 v[76:79], v[150:153], v[216:219], v[76:79]
	v_mfma_f32_16x16x32_bf16 v[72:75], v[158:161], v[216:219], v[72:75]
	s_setprio 0
	s_setprio 1
	v_mfma_f32_16x16x32_bf16 v[116:119], v[168:171], v[184:187], 0
	v_mfma_f32_16x16x32_bf16 v[112:115], v[176:179], v[184:187], 0
	v_mfma_f32_16x16x32_bf16 v[100:103], v[168:171], v[192:195], 0
	v_mfma_f32_16x16x32_bf16 v[96:99], v[176:179], v[192:195], 0
	v_mfma_f32_16x16x32_bf16 v[84:87], v[168:171], v[200:203], 0
	v_mfma_f32_16x16x32_bf16 v[80:83], v[176:179], v[200:203], 0
	v_mfma_f32_16x16x32_bf16 v[68:71], v[168:171], v[208:211], 0
	v_mfma_f32_16x16x32_bf16 v[64:67], v[176:179], v[208:211], 0
	v_mfma_f32_16x16x32_bf16 v[116:119], v[172:175], v[188:191], v[116:119]
	v_mfma_f32_16x16x32_bf16 v[112:115], v[180:183], v[188:191], v[112:115]
	v_mfma_f32_16x16x32_bf16 v[100:103], v[172:175], v[196:199], v[100:103]
	v_mfma_f32_16x16x32_bf16 v[96:99], v[180:183], v[196:199], v[96:99]
	v_mfma_f32_16x16x32_bf16 v[84:87], v[172:175], v[204:207], v[84:87]
	v_mfma_f32_16x16x32_bf16 v[80:83], v[180:183], v[204:207], v[80:83]
	v_mfma_f32_16x16x32_bf16 v[68:71], v[172:175], v[216:219], v[68:71]
	v_mfma_f32_16x16x32_bf16 v[64:67], v[180:183], v[216:219], v[64:67]
	s_setprio 0
	s_barrier
	s_add_i32 s71, s82, s94
	v_lshl_add_u64 v[212:213], s[64:65], 0, v[130:131]
	s_mov_b32 m0, s71
	ds_read_b128 v[184:187], v165 offset:16384
	ds_read_b128 v[188:191], v165 offset:17408
	ds_read_b128 v[192:195], v165 offset:18432
	ds_read_b128 v[196:199], v165 offset:19456
	ds_read_b128 v[200:203], v165 offset:20480
	ds_read_b128 v[204:207], v165 offset:21504
	ds_read_b128 v[208:211], v165 offset:22528
	ds_read_b128 v[216:219], v165 offset:23552
	global_load_lds_dwordx4 v[212:213], off
	s_add_i32 m0, s71, 0x2000
	s_add_u32 s86, s64, 0x40000
	v_lshl_add_u64 v[214:215], s[64:65], 0, v[134:135]
	s_addc_u32 s87, s65, 0
	s_add_i32 s71, s83, s94
	global_load_lds_dwordx4 v[214:215], off
	v_lshl_add_u64 v[220:221], s[86:87], 0, v[130:131]
	s_mov_b32 m0, s71
	v_lshl_add_u64 v[222:223], s[66:67], 0, v[132:133]
	global_load_lds_dwordx4 v[220:221], off
	v_lshl_add_u64 v[220:221], s[86:87], 0, v[134:135]
	s_add_i32 m0, s71, 0x2000
	s_nop 0
	global_load_lds_dwordx4 v[220:221], off
	v_lshl_add_u64 v[220:221], s[66:67], 0, v[128:129]
	s_mov_b32 m0, s6
	s_nop 0
	global_load_lds_dwordx4 v[220:221], off
	s_mov_b32 m0, s7
	s_nop 0
	global_load_lds_dwordx4 v[222:223], off
	s_add_i32 s85, s85, 1
	s_mul_i32 s8, s85, s78
	s_mul_hi_u32 s9, s85, s79
	s_add_i32 s9, s9, s8
	s_mul_i32 s8, s85, s79
	s_add_u32 s60, s8, s2
	s_addc_u32 s61, s9, s3
	v_cmp_lt_i64_e64 s[8:9], s[60:61], v[142:143]
	s_mul_i32 s57, s61, 0xaaaaaaab
	s_mul_hi_u32 s58, s60, 0xaaaaaaab
	s_mul_hi_u32 s56, s61, 0xaaaaaaab
	s_add_u32 s57, s57, s58
	s_mul_i32 s16, s60, 0x2aaaaaaa
	s_addc_u32 s56, s56, 0
	s_mul_hi_u32 s11, s60, 0x2aaaaaaa
	s_add_u32 s16, s16, s57
	s_addc_u32 s11, s11, 0
	s_add_u32 s11, s56, s11
	s_addc_u32 s16, 0, 0
	s_mul_i32 s57, s61, 0x2aaaaaaa
	s_mul_hi_u32 s56, s61, 0x2aaaaaaa
	s_add_u32 s11, s57, s11
	s_addc_u32 s16, s56, s16
	s_ashr_i32 s56, s61, 31
	s_mul_i32 s57, s56, 0x2aaaaaaa
	s_mul_hi_u32 s58, s56, 0xaaaaaaab
	s_add_i32 s57, s58, s57
	s_mul_i32 s56, s56, 0xaaaaaaab
	s_add_i32 s57, s57, s56
	s_add_u32 s56, s11, s56
	s_addc_u32 s57, s16, s57
	s_ashr_i64 s[58:59], s[56:57], 9
	s_lshr_b32 s11, s57, 31
	s_add_u32 s11, s58, s11
	s_mulk_i32 s11, 0xc00
	s_sub_i32 s11, s60, s11
	s_sext_i32_i16 s16, s11
	s_bfe_u32 s16, s16, 0x3001c
	s_add_i32 s16, s11, s16
	s_sext_i32_i16 s56, s16
	s_waitcnt vmcnt(8)
	s_waitcnt lgkmcnt(0)
	s_barrier
; #define PG8_STAGE(bufoff, gbase, voff) do { _Pragma("unroll") for (int _i = 0; _i < 2; ++_i) \
;         __builtin_amdgcn_global_load_lds((const unsigned*)((const char*)(gbase) + (voff)[_i]), (LAS unsigned*)(lds + (bufoff) + ldsw + _i * 8192), 16, 0, 0); } while (0)
; #define PG8_LDA(dst, b, h) do { _Pragma("unroll") for (int m = 0; m < 4; ++m) _Pragma("unroll") for (int k = 0; k < 2; ++k) dst[m][k] = *(const LAS bf16x8*)(lds + PG8_SA(b, h) + aoff + m * 2048 + k * 1024); } while (0)
; #define PG8_LDB(dst, b, h) do { _Pragma("unroll") for (int n = 0; n < 2; ++n) _Pragma("unroll") for (int k = 0; k < 2; ++k) dst[n][k] = *(const LAS bf16x8*)(lds + PG8_SB(b, h) + boff + n * 2048 + k * 1024); } while (0)
; #define PG8_MMA(ai, bj, At, Bt) do { __builtin_amdgcn_s_setprio(1); _Pragma("unroll") for (int m = 0; m < 4; ++m) _Pragma("unroll") for (int n = 0; n < 2; ++n) _Pragma("unroll") for (int k = 0; k < 2; ++k) \
;         acc[ai][bj][m][n] = __builtin_amdgcn_mfma_f32_16x16x32_bf16(Bt[n][k], At[m][k], acc[ai][bj][m][n], 0, 0, 0); __builtin_amdgcn_s_setprio(0); } while (0)
; #define PG8_WAIT_V(n) asm volatile("s_waitcnt vmcnt(" #n ")" ::: "memory")
; #define PG8_WAIT_L(n) asm volatile("s_waitcnt lgkmcnt(" #n ")" ::: "memory")
; #define PG8_BAR __builtin_amdgcn_s_barrier()
; #define PG8_SCHED __builtin_amdgcn_sched_barrier(0)
;     DI bool next(int i, Unit& u) const {
;     ...
;         { const int q = nwg / NXCD, r = nwg % NXCD, xcd = wgid % NXCD, off = wgid / NXCD; wgid = (xcd < r ? xcd * (q + 1) : r * (q + 1) + (xcd - r) * q) + off; }
;         const int nig = WGM * nN, gid = wgid / nig, fm = gid * WGM, gsz = (nM - fm) < WGM ? (nM - fm) : WGM;
;         u.pm = fm + ((wgid % nig) % gsz); u.pn = (wgid % nig) / gsz; return true;
;     }
; template <class Epi>
; DI void gemm_phase(LAS unsigned char* lds, const int wid, const Gemm g, const Order& S, const Epi& E) {
;     ...
;             PG8_WAIT_V(8); PG8_WAIT_L(0); PG8_BAR; PG8_MMA(1, 0, At, B0); PG8_MMA(1, 1, At, B1); PG8_BAR; PG8_SCHED;
;             PG8_LDB(B0, 1, 0); PG8_LDB(B1, 1, 1); PG8_SCHED; PG8_LDA(At, 1, 0); PG8_STAGE(PG8_SA(0, 1), a2 + hstepA, voffA);
	s_setprio 1
	s_waitcnt lgkmcnt(0)
	v_mfma_f32_16x16x32_bf16 v[60:63], v[146:149], v[184:187], 0
	v_mfma_f32_16x16x32_bf16 v[56:59], v[154:157], v[184:187], 0
	v_mfma_f32_16x16x32_bf16 v[44:47], v[146:149], v[192:195], 0
	v_mfma_f32_16x16x32_bf16 v[40:43], v[154:157], v[192:195], 0
	v_mfma_f32_16x16x32_bf16 v[28:31], v[146:149], v[200:203], 0
	v_mfma_f32_16x16x32_bf16 v[24:27], v[154:157], v[200:203], 0
	v_mfma_f32_16x16x32_bf16 v[12:15], v[146:149], v[208:211], 0
	v_mfma_f32_16x16x32_bf16 v[8:11], v[154:157], v[208:211], 0
	v_mfma_f32_16x16x32_bf16 v[60:63], v[150:153], v[188:191], v[60:63]
	v_mfma_f32_16x16x32_bf16 v[56:59], v[158:161], v[188:191], v[56:59]
	v_mfma_f32_16x16x32_bf16 v[44:47], v[150:153], v[196:199], v[44:47]
	v_mfma_f32_16x16x32_bf16 v[40:43], v[158:161], v[196:199], v[40:43]
	v_mfma_f32_16x16x32_bf16 v[28:31], v[150:153], v[204:207], v[28:31]
	v_mfma_f32_16x16x32_bf16 v[24:27], v[158:161], v[204:207], v[24:27]
	v_mfma_f32_16x16x32_bf16 v[12:15], v[150:153], v[216:219], v[12:15]
	v_mfma_f32_16x16x32_bf16 v[8:11], v[158:161], v[216:219], v[8:11]
	s_setprio 0
	s_setprio 1
	v_mfma_f32_16x16x32_bf16 v[52:55], v[168:171], v[184:187], 0
	v_mfma_f32_16x16x32_bf16 v[48:51], v[176:179], v[184:187], 0
	v_mfma_f32_16x16x32_bf16 v[36:39], v[168:171], v[192:195], 0
	v_mfma_f32_16x16x32_bf16 v[32:35], v[176:179], v[192:195], 0
	v_mfma_f32_16x16x32_bf16 v[20:23], v[168:171], v[200:203], 0
	v_mfma_f32_16x16x32_bf16 v[16:19], v[176:179], v[200:203], 0
	v_mfma_f32_16x16x32_bf16 v[4:7], v[168:171], v[208:211], 0
	v_mfma_f32_16x16x32_bf16 v[0:3], v[176:179], v[208:211], 0
	v_mfma_f32_16x16x32_bf16 v[52:55], v[172:175], v[188:191], v[52:55]
	v_mfma_f32_16x16x32_bf16 v[48:51], v[180:183], v[188:191], v[48:51]
	v_mfma_f32_16x16x32_bf16 v[36:39], v[172:175], v[196:199], v[36:39]
	v_mfma_f32_16x16x32_bf16 v[32:35], v[180:183], v[196:199], v[32:35]
	v_mfma_f32_16x16x32_bf16 v[20:23], v[172:175], v[204:207], v[20:23]
	v_mfma_f32_16x16x32_bf16 v[16:19], v[180:183], v[204:207], v[16:19]
	v_mfma_f32_16x16x32_bf16 v[4:7], v[172:175], v[216:219], v[4:7]
	v_mfma_f32_16x16x32_bf16 v[0:3], v[180:183], v[216:219], v[0:3]
	s_setprio 0
	s_barrier
	s_add_i32 s71, 0, 0x18000
	v_add_u32_e32 v136, s71, v162
	s_add_i32 s86, 0, 0x1c000
	ds_read_b128 v[146:149], v136
	ds_read_b128 v[150:153], v136 offset:1024
	ds_read_b128 v[154:157], v136 offset:2048
	ds_read_b128 v[158:161], v136 offset:3072
	v_add_u32_e32 v136, s86, v162
	ds_read_b128 v[168:171], v136
	ds_read_b128 v[172:175], v136 offset:1024
	ds_read_b128 v[176:179], v136 offset:2048
	ds_read_b128 v[180:183], v136 offset:3072
	s_add_u32 s66, s66, 0x40000
	s_addc_u32 s67, s67, 0
	s_mov_b32 m0, s21
	v_lshl_add_u64 v[224:225], s[66:67], 0, v[128:129]
	ds_read_b128 v[184:187], v165 offset:32768
	ds_read_b128 v[188:191], v165 offset:33792
	ds_read_b128 v[192:195], v165 offset:34816
	ds_read_b128 v[196:199], v165 offset:35840
	ds_read_b128 v[200:203], v165 offset:36864
	ds_read_b128 v[204:207], v165 offset:37888
	ds_read_b128 v[208:211], v165 offset:38912
	ds_read_b128 v[216:219], v165 offset:39936
	global_load_lds_dwordx4 v[224:225], off
	v_lshl_add_u64 v[224:225], s[66:67], 0, v[132:133]
	s_mov_b32 m0, s26
	s_nop 0
	global_load_lds_dwordx4 v[224:225], off
	s_and_b32 s16, s16, 0xfff8
	s_sub_i32 s11, s11, s16
	s_ashr_i32 s56, s56, 3
	s_sext_i32_i16 s16, s11
	s_cmp_lt_i32 s16, 0
	s_movk_i32 s16, 0x181
	s_cselect_b32 s16, s16, 0x180
	s_mul_i32 s11, s11, s16
	s_add_i32 s11, s11, s56
	s_sext_i32_i16 s16, s11
	s_mulk_i32 s16, 0x2aab
	s_lshr_b32 s56, s16, 31
	s_ashr_i32 s16, s16, 20
	s_add_i32 s16, s16, s56
	s_lshl_b32 s56, s16, 3
	s_mulk_i32 s16, 0x60
	s_sub_i32 s11, s11, s16
	s_bfe_i32 s16, s11, 0x80000
	s_bfe_u32 s16, s16, 0x3000c
	s_add_i32 s16, s11, s16
	s_bfe_i32 s57, s16, 0x80000
	s_and_b32 s16, s16, 0xf8
	s_sub_i32 s11, s11, s16
	s_sext_i32_i16 s57, s57
	s_sext_i32_i8 s11, s11
	s_add_i32 s56, s56, s11
	s_ashr_i32 s58, s57, 3
	s_ashr_i32 s57, s56, 31
	s_lshl_b64 s[60:61], s[56:57], 19
	s_add_u32 s60, s73, s60
	s_addc_u32 s61, s74, s61
	s_and_b64 s[62:63], s[8:9], exec
	s_cselect_b32 s11, s61, s13
	s_cselect_b32 s16, s60, s12
	s_ashr_i32 s59, s58, 31
	s_lshl_b64 s[62:63], s[58:59], 19
	s_add_u32 s62, s75, s62
	s_addc_u32 s63, s76, s63
	s_and_b64 vcc, s[8:9], exec
	s_cselect_b32 s57, s63, s65
	s_cselect_b32 s59, s62, s64
	s_waitcnt vmcnt(8)
	s_waitcnt lgkmcnt(0)
	s_barrier
; #define PG8_STAGE(bufoff, gbase, voff) do { _Pragma("unroll") for (int _i = 0; _i < 2; ++_i) \
;         __builtin_amdgcn_global_load_lds((const unsigned*)((const char*)(gbase) + (voff)[_i]), (LAS unsigned*)(lds + (bufoff) + ldsw + _i * 8192), 16, 0, 0); } while (0)
; #define PG8_LDA(dst, b, h) do { _Pragma("unroll") for (int m = 0; m < 4; ++m) _Pragma("unroll") for (int k = 0; k < 2; ++k) dst[m][k] = *(const LAS bf16x8*)(lds + PG8_SA(b, h) + aoff + m * 2048 + k * 1024); } while (0)
; #define PG8_MMA(ai, bj, At, Bt) do { __builtin_amdgcn_s_setprio(1); _Pragma("unroll") for (int m = 0; m < 4; ++m) _Pragma("unroll") for (int n = 0; n < 2; ++n) _Pragma("unroll") for (int k = 0; k < 2; ++k) \
;         acc[ai][bj][m][n] = __builtin_amdgcn_mfma_f32_16x16x32_bf16(Bt[n][k], At[m][k], acc[ai][bj][m][n], 0, 0, 0); __builtin_amdgcn_s_setprio(0); } while (0)
; #define PG8_WAIT_V(n) asm volatile("s_waitcnt vmcnt(" #n ")" ::: "memory")
; #define PG8_WAIT_L(n) asm volatile("s_waitcnt lgkmcnt(" #n ")" ::: "memory")
; #define PG8_BAR __builtin_amdgcn_s_barrier()
; #define PG8_SCHED __builtin_amdgcn_sched_barrier(0)
; template <class Epi>
; DI void gemm_phase(LAS unsigned char* lds, const int wid, const Gemm g, const Order& S, const Epi& E) {
;     ...
;             PG8_WAIT_V(8); PG8_WAIT_L(0); PG8_BAR; PG8_MMA(0, 0, At, B0); PG8_MMA(0, 1, At, B1); PG8_BAR; PG8_SCHED;
;             PG8_LDA(At, 1, 1); PG8_STAGE(PG8_SB(1, 0), b3, voffB); PG8_STAGE(PG8_SB(1, 1), b3 + hstepB, voffB); PG8_STAGE(PG8_SA(1, 0), a3, voffA);
;             PG8_WAIT_V(8); PG8_WAIT_L(0); PG8_BAR; PG8_MMA(1, 0, At, B0); PG8_MMA(1, 1, At, B1); PG8_BAR; PG8_SCHED;
	s_setprio 1
	s_waitcnt lgkmcnt(0)
	v_mfma_f32_16x16x32_bf16 v[124:127], v[146:149], v[184:187], v[124:127]
	v_mfma_f32_16x16x32_bf16 v[120:123], v[154:157], v[184:187], v[120:123]
	v_mfma_f32_16x16x32_bf16 v[108:111], v[146:149], v[192:195], v[108:111]
	v_mfma_f32_16x16x32_bf16 v[104:107], v[154:157], v[192:195], v[104:107]
	v_mfma_f32_16x16x32_bf16 v[92:95], v[146:149], v[200:203], v[92:95]
	v_mfma_f32_16x16x32_bf16 v[88:91], v[154:157], v[200:203], v[88:91]
	v_mfma_f32_16x16x32_bf16 v[76:79], v[146:149], v[208:211], v[76:79]
	v_mfma_f32_16x16x32_bf16 v[72:75], v[154:157], v[208:211], v[72:75]
	v_mfma_f32_16x16x32_bf16 v[124:127], v[150:153], v[188:191], v[124:127]
	v_mfma_f32_16x16x32_bf16 v[120:123], v[158:161], v[188:191], v[120:123]
	v_mfma_f32_16x16x32_bf16 v[108:111], v[150:153], v[196:199], v[108:111]
	v_mfma_f32_16x16x32_bf16 v[104:107], v[158:161], v[196:199], v[104:107]
	v_mfma_f32_16x16x32_bf16 v[92:95], v[150:153], v[204:207], v[92:95]
	v_mfma_f32_16x16x32_bf16 v[88:91], v[158:161], v[204:207], v[88:91]
	v_mfma_f32_16x16x32_bf16 v[76:79], v[150:153], v[216:219], v[76:79]
	v_mfma_f32_16x16x32_bf16 v[72:75], v[158:161], v[216:219], v[72:75]
	s_setprio 0
	s_setprio 1
	v_mfma_f32_16x16x32_bf16 v[116:119], v[168:171], v[184:187], v[116:119]
	v_mfma_f32_16x16x32_bf16 v[112:115], v[176:179], v[184:187], v[112:115]
	v_mfma_f32_16x16x32_bf16 v[100:103], v[168:171], v[192:195], v[100:103]
	v_mfma_f32_16x16x32_bf16 v[96:99], v[176:179], v[192:195], v[96:99]
	v_mfma_f32_16x16x32_bf16 v[84:87], v[168:171], v[200:203], v[84:87]
	v_mfma_f32_16x16x32_bf16 v[80:83], v[176:179], v[200:203], v[80:83]
	v_mfma_f32_16x16x32_bf16 v[68:71], v[168:171], v[208:211], v[68:71]
	v_mfma_f32_16x16x32_bf16 v[64:67], v[176:179], v[208:211], v[64:67]
	v_mfma_f32_16x16x32_bf16 v[116:119], v[172:175], v[188:191], v[116:119]
	v_mfma_f32_16x16x32_bf16 v[112:115], v[180:183], v[188:191], v[112:115]
	v_mfma_f32_16x16x32_bf16 v[100:103], v[172:175], v[196:199], v[100:103]
	v_mfma_f32_16x16x32_bf16 v[96:99], v[180:183], v[196:199], v[96:99]
	v_mfma_f32_16x16x32_bf16 v[84:87], v[172:175], v[204:207], v[84:87]
	v_mfma_f32_16x16x32_bf16 v[80:83], v[180:183], v[204:207], v[80:83]
	v_mfma_f32_16x16x32_bf16 v[68:71], v[172:175], v[216:219], v[68:71]
	v_mfma_f32_16x16x32_bf16 v[64:67], v[180:183], v[216:219], v[64:67]
	s_setprio 0
	s_barrier
	s_add_i32 s66, s71, s94
	v_lshl_add_u64 v[212:213], v[212:213], 0, s[34:35]
	s_mov_b32 m0, s66
	ds_read_b128 v[184:187], v165 offset:49152
	ds_read_b128 v[188:191], v165 offset:50176
	ds_read_b128 v[192:195], v165 offset:51200
	ds_read_b128 v[196:199], v165 offset:52224
	ds_read_b128 v[200:203], v165 offset:53248
	ds_read_b128 v[204:207], v165 offset:54272
	ds_read_b128 v[208:211], v165 offset:55296
	ds_read_b128 v[216:219], v165 offset:56320
	global_load_lds_dwordx4 v[212:213], off
	s_add_i32 m0, s66, 0x2000
	s_add_u32 s64, s64, 0x40080
	v_lshl_add_u64 v[212:213], v[214:215], 0, s[34:35]
	s_addc_u32 s65, s65, 0
	s_add_i32 s66, s86, s94
	global_load_lds_dwordx4 v[212:213], off
	v_lshl_add_u64 v[212:213], s[64:65], 0, v[130:131]
	s_mov_b32 m0, s66
	s_nop 0
	global_load_lds_dwordx4 v[212:213], off
	v_lshl_add_u64 v[212:213], s[64:65], 0, v[134:135]
	s_add_i32 m0, s66, 0x2000
	s_nop 0
	global_load_lds_dwordx4 v[212:213], off
	v_lshl_add_u64 v[212:213], v[220:221], 0, s[34:35]
	s_mov_b32 m0, s27
	s_nop 0
	global_load_lds_dwordx4 v[212:213], off
	v_lshl_add_u64 v[212:213], v[222:223], 0, s[34:35]
	s_mov_b32 m0, s55
	s_nop 0
	global_load_lds_dwordx4 v[212:213], off
	s_waitcnt vmcnt(8)
	s_waitcnt lgkmcnt(0)
	s_barrier
	s_setprio 1
	s_waitcnt lgkmcnt(0)
	v_mfma_f32_16x16x32_bf16 v[60:63], v[146:149], v[184:187], v[60:63]
	v_mfma_f32_16x16x32_bf16 v[56:59], v[154:157], v[184:187], v[56:59]
	v_mfma_f32_16x16x32_bf16 v[44:47], v[146:149], v[192:195], v[44:47]
	v_mfma_f32_16x16x32_bf16 v[40:43], v[154:157], v[192:195], v[40:43]
	v_mfma_f32_16x16x32_bf16 v[28:31], v[146:149], v[200:203], v[28:31]
	v_mfma_f32_16x16x32_bf16 v[24:27], v[154:157], v[200:203], v[24:27]
	v_mfma_f32_16x16x32_bf16 v[12:15], v[146:149], v[208:211], v[12:15]
	v_mfma_f32_16x16x32_bf16 v[8:11], v[154:157], v[208:211], v[8:11]
	v_mfma_f32_16x16x32_bf16 v[60:63], v[150:153], v[188:191], v[60:63]
	v_mfma_f32_16x16x32_bf16 v[56:59], v[158:161], v[188:191], v[56:59]
	v_mfma_f32_16x16x32_bf16 v[44:47], v[150:153], v[196:199], v[44:47]
	v_mfma_f32_16x16x32_bf16 v[40:43], v[158:161], v[196:199], v[40:43]
	v_mfma_f32_16x16x32_bf16 v[28:31], v[150:153], v[204:207], v[28:31]
	v_mfma_f32_16x16x32_bf16 v[24:27], v[158:161], v[204:207], v[24:27]
	v_mfma_f32_16x16x32_bf16 v[12:15], v[150:153], v[216:219], v[12:15]
	v_mfma_f32_16x16x32_bf16 v[8:11], v[158:161], v[216:219], v[8:11]
	s_setprio 0
	s_setprio 1
	v_mfma_f32_16x16x32_bf16 v[52:55], v[168:171], v[184:187], v[52:55]
	v_mfma_f32_16x16x32_bf16 v[48:51], v[176:179], v[184:187], v[48:51]
	v_mfma_f32_16x16x32_bf16 v[36:39], v[168:171], v[192:195], v[36:39]
	v_mfma_f32_16x16x32_bf16 v[32:35], v[176:179], v[192:195], v[32:35]
	v_mfma_f32_16x16x32_bf16 v[20:23], v[168:171], v[200:203], v[20:23]
	v_mfma_f32_16x16x32_bf16 v[16:19], v[176:179], v[200:203], v[16:19]
	v_mfma_f32_16x16x32_bf16 v[4:7], v[168:171], v[208:211], v[4:7]
	v_mfma_f32_16x16x32_bf16 v[0:3], v[176:179], v[208:211], v[0:3]
	v_mfma_f32_16x16x32_bf16 v[52:55], v[172:175], v[188:191], v[52:55]
	v_mfma_f32_16x16x32_bf16 v[48:51], v[180:183], v[188:191], v[48:51]
	v_mfma_f32_16x16x32_bf16 v[36:39], v[172:175], v[196:199], v[36:39]
	v_mfma_f32_16x16x32_bf16 v[32:35], v[180:183], v[196:199], v[32:35]
	v_mfma_f32_16x16x32_bf16 v[20:23], v[172:175], v[204:207], v[20:23]
	v_mfma_f32_16x16x32_bf16 v[16:19], v[180:183], v[204:207], v[16:19]
	v_mfma_f32_16x16x32_bf16 v[4:7], v[172:175], v[216:219], v[4:7]
	v_mfma_f32_16x16x32_bf16 v[0:3], v[180:183], v[216:219], v[0:3]
	s_setprio 0
	s_barrier
	s_add_i32 s70, s70, 2
	s_add_u32 s12, s12, 0x100
	s_addc_u32 s13, s13, 0
	s_add_u32 s68, s68, 0x100
	s_addc_u32 s69, s69, 0
	s_cmp_gt_u32 s70, 13
	s_cbranch_scc0 .LBB0_400
	s_branch .Lpeel_exit_2

; #define PG8_STAGE(bufoff, gbase, voff) do { _Pragma("unroll") for (int _i = 0; _i < 2; ++_i) \
;         __builtin_amdgcn_global_load_lds((const unsigned*)((const char*)(gbase) + (voff)[_i]), (LAS unsigned*)(lds + (bufoff) + ldsw + _i * 8192), 16, 0, 0); } while (0)
; #define PG8_LDA(dst, b, h) do { _Pragma("unroll") for (int m = 0; m < 4; ++m) _Pragma("unroll") for (int k = 0; k < 2; ++k) dst[m][k] = *(const LAS bf16x8*)(lds + PG8_SA(b, h) + aoff + m * 2048 + k * 1024); } while (0)
; #define PG8_WAIT_V(n) asm volatile("s_waitcnt vmcnt(" #n ")" ::: "memory")
; #define PG8_WAIT_L(n) asm volatile("s_waitcnt lgkmcnt(" #n ")" ::: "memory")
;     DI bool next(int i, Unit& u) const {
;         const long L = (long)i * G + c; if (L >= total) return false;
;         u.g = (int)(L / nwg); int wgid = (int)(L % nwg);
;         { const int q = nwg / NXCD, r = nwg % NXCD, xcd = wgid % NXCD, off = wgid / NXCD; wgid = (xcd < r ? xcd * (q + 1) : r * (q + 1) + (xcd - r) * q) + off; }
;         const int nig = WGM * nN, gid = wgid / nig, fm = gid * WGM, gsz = (nM - fm) < WGM ? (nM - fm) : WGM;
;         u.pm = fm + ((wgid % nig) % gsz); u.pn = (wgid % nig) / gsz; return true;
;     }
; template <class Epi>
; DI void gemm_phase(LAS unsigned char* lds, const int wid, const Gemm g, const Order& S, const Epi& E) {
;     ...
;         const bool has_next = S.next(ui + 1, nxt);
;         const char* nA = has_next ? (const char*)(g.A + (size_t)nxt.g * g.gsA + (size_t)nxt.pm * BM * g.lda) : cA;
;         const char* nB = has_next ? (const char*)(g.Bt + (size_t)nxt.g * g.gsB + (size_t)nxt.pn * BM * g.ldb) : cB;
;         for (int t = 0; t < nt; t += 2) {
;             const bool last = (t == nt - 2);
;             const char* a1 = cA + (size_t)(t + 1) * kstep;
;             const char* a2 = last ? nA : cA + (size_t)(t + 2) * kstep; const char* b2 = last ? nB : cB + (size_t)(t + 2) * kstep;
;             const char* a3 = a2 + kstep; const char* b3 = b2 + kstep;
;             PG8_LDB(B0, 0, 0); PG8_LDB(B1, 0, 1); PG8_SCHED; PG8_LDA(At, 0, 0); PG8_STAGE(PG8_SA(1, 1), a1 + hstepA, voffA);
;             PG8_WAIT_V(8); PG8_WAIT_L(0); PG8_BAR; PG8_MMA(0, 0, At, B0); PG8_MMA(0, 1, At, B1); PG8_BAR; PG8_SCHED;
;             PG8_LDA(At, 0, 1); PG8_STAGE(PG8_SB(0, 0), b2, voffB); PG8_STAGE(PG8_SB(0, 1), b2 + hstepB, voffB); PG8_STAGE(PG8_SA(0, 0), a2, voffA);
.LBB0_1333:
.LBB0_1335:
	s_add_u32 s38, s38, 0x40080
	s_addc_u32 s39, s39, 0
	s_add_u32 s58, s40, 0x100
	v_mov_b32_e32 v0, 0
	s_addc_u32 s59, s41, 0
	s_mov_b32 s60, -2
	ds_read_b128 v[164:167], v151
	ds_read_b128 v[168:171], v151 offset:1024
	ds_read_b128 v[172:175], v151 offset:2048
	ds_read_b128 v[176:179], v151 offset:3072
	ds_read_b128 v[180:183], v155
	ds_read_b128 v[184:187], v155 offset:1024
	ds_read_b128 v[188:191], v155 offset:2048
	ds_read_b128 v[192:195], v155 offset:3072
	s_add_u32 s40, s38, 0xfffc0080
	s_addc_u32 s41, s39, -1
	s_cmp_eq_u32 s60, 12
	s_cselect_b32 s43, s27, s41
	s_cselect_b32 s42, s56, s40
	s_cselect_b32 s41, s29, s59
	s_cselect_b32 s40, s57, s58
	v_lshl_add_u64 v[144:145], s[38:39], 0, v[136:137]
	s_add_i32 m0, s37, 0xc000
	ds_read_b128 v[196:199], v159
	ds_read_b128 v[200:203], v159 offset:1024
	ds_read_b128 v[204:207], v159 offset:2048
	ds_read_b128 v[208:211], v159 offset:3072
	ds_read_b128 v[212:215], v159 offset:4096
	ds_read_b128 v[216:219], v159 offset:5120
	ds_read_b128 v[220:223], v159 offset:6144
	ds_read_b128 v[224:227], v159 offset:7168
	global_load_lds_dwordx4 v[144:145], off
	v_lshl_add_u64 v[144:145], s[38:39], 0, v[138:139]
	s_add_i32 m0, s37, 0xe000
	s_nop 0
	global_load_lds_dwordx4 v[144:145], off
	s_waitcnt vmcnt(8)
	s_waitcnt lgkmcnt(0)
	s_barrier
	s_setprio 1
	s_waitcnt lgkmcnt(0)
	v_mfma_f32_16x16x32_bf16 v[124:127], v[164:167], v[196:199], 0
	v_mfma_f32_16x16x32_bf16 v[120:123], v[172:175], v[196:199], 0
	v_mfma_f32_16x16x32_bf16 v[108:111], v[164:167], v[204:207], 0
	v_mfma_f32_16x16x32_bf16 v[104:107], v[172:175], v[204:207], 0
	v_mfma_f32_16x16x32_bf16 v[92:95], v[164:167], v[212:215], 0
	v_mfma_f32_16x16x32_bf16 v[88:91], v[172:175], v[212:215], 0
	v_mfma_f32_16x16x32_bf16 v[76:79], v[164:167], v[220:223], 0
	v_mfma_f32_16x16x32_bf16 v[72:75], v[172:175], v[220:223], 0
	v_mfma_f32_16x16x32_bf16 v[124:127], v[168:171], v[200:203], v[124:127]
	v_mfma_f32_16x16x32_bf16 v[120:123], v[176:179], v[200:203], v[120:123]
	v_mfma_f32_16x16x32_bf16 v[108:111], v[168:171], v[208:211], v[108:111]
	v_mfma_f32_16x16x32_bf16 v[104:107], v[176:179], v[208:211], v[104:107]
	v_mfma_f32_16x16x32_bf16 v[92:95], v[168:171], v[216:219], v[92:95]
	v_mfma_f32_16x16x32_bf16 v[88:91], v[176:179], v[216:219], v[88:91]
	v_mfma_f32_16x16x32_bf16 v[76:79], v[168:171], v[224:227], v[76:79]
	v_mfma_f32_16x16x32_bf16 v[72:75], v[176:179], v[224:227], v[72:75]
	s_setprio 0
	s_setprio 1
	v_mfma_f32_16x16x32_bf16 v[116:119], v[180:183], v[196:199], 0
	v_mfma_f32_16x16x32_bf16 v[112:115], v[188:191], v[196:199], 0
	v_mfma_f32_16x16x32_bf16 v[100:103], v[180:183], v[204:207], 0
	v_mfma_f32_16x16x32_bf16 v[96:99], v[188:191], v[204:207], 0
	v_mfma_f32_16x16x32_bf16 v[84:87], v[180:183], v[212:215], 0
	v_mfma_f32_16x16x32_bf16 v[80:83], v[188:191], v[212:215], 0
	v_mfma_f32_16x16x32_bf16 v[68:71], v[180:183], v[220:223], 0
	v_mfma_f32_16x16x32_bf16 v[64:67], v[188:191], v[220:223], 0
	v_mfma_f32_16x16x32_bf16 v[116:119], v[184:187], v[200:203], v[116:119]
	v_mfma_f32_16x16x32_bf16 v[112:115], v[192:195], v[200:203], v[112:115]
	v_mfma_f32_16x16x32_bf16 v[100:103], v[184:187], v[208:211], v[100:103]
	v_mfma_f32_16x16x32_bf16 v[96:99], v[192:195], v[208:211], v[96:99]
	v_mfma_f32_16x16x32_bf16 v[84:87], v[184:187], v[216:219], v[84:87]
	v_mfma_f32_16x16x32_bf16 v[80:83], v[192:195], v[216:219], v[80:83]
	v_mfma_f32_16x16x32_bf16 v[68:71], v[184:187], v[224:227], v[68:71]
	v_mfma_f32_16x16x32_bf16 v[64:67], v[192:195], v[224:227], v[64:67]
	s_setprio 0
	s_barrier
	s_add_i32 s61, s53, s94
	v_lshl_add_u64 v[144:145], s[40:41], 0, v[132:133]
	s_mov_b32 m0, s61
	ds_read_b128 v[196:199], v159 offset:16384
	ds_read_b128 v[200:203], v159 offset:17408
	ds_read_b128 v[204:207], v159 offset:18432
	ds_read_b128 v[208:211], v159 offset:19456
	ds_read_b128 v[212:215], v159 offset:20480
	ds_read_b128 v[216:219], v159 offset:21504
	ds_read_b128 v[220:223], v159 offset:22528
	ds_read_b128 v[224:227], v159 offset:23552
	global_load_lds_dwordx4 v[144:145], off
	s_add_i32 m0, s61, 0x2000
	s_add_u32 s62, s40, 0x40000
	v_lshl_add_u64 v[148:149], s[40:41], 0, v[128:129]
	s_addc_u32 s63, s41, 0
	s_add_i32 s61, s54, s94
	global_load_lds_dwordx4 v[148:149], off
	v_lshl_add_u64 v[152:153], s[62:63], 0, v[132:133]
	s_mov_b32 m0, s61
	v_lshl_add_u64 v[156:157], s[42:43], 0, v[130:131]
	global_load_lds_dwordx4 v[152:153], off
	v_lshl_add_u64 v[152:153], s[62:63], 0, v[128:129]
	s_add_i32 m0, s61, 0x2000
	s_nop 0
	global_load_lds_dwordx4 v[152:153], off
	v_lshl_add_u64 v[152:153], s[42:43], 0, v[134:135]
	s_mov_b32 m0, s37
	s_nop 0
	global_load_lds_dwordx4 v[152:153], off
	s_mov_b32 m0, s46
	s_nop 0
	global_load_lds_dwordx4 v[156:157], off
	s_add_i32 s50, s50, 1
	s_mul_i32 s8, s50, s33
	s_mul_hi_u32 s9, s50, s64
	s_add_i32 s9, s9, s8
	s_mul_i32 s8, s50, s64
	s_add_u32 s30, s8, s2
	s_addc_u32 s31, s9, s3
	v_cmp_lt_i64_e64 s[8:9], s[30:31], v[140:141]
	s_mul_i32 s29, s31, 0xba2e8ba3
	s_mul_hi_u32 s34, s30, 0xba2e8ba3
	s_mul_hi_u32 s28, s31, 0xba2e8ba3
	s_add_u32 s29, s29, s34
	s_mul_i32 s27, s30, 0x2e8ba2e8
	s_addc_u32 s28, s28, 0
	s_mul_hi_u32 s26, s30, 0x2e8ba2e8
	s_add_u32 s27, s27, s29
	s_addc_u32 s26, s26, 0
	s_add_u32 s26, s28, s26
	s_addc_u32 s27, 0, 0
	s_mul_i32 s29, s31, 0x2e8ba2e8
	s_mul_hi_u32 s28, s31, 0x2e8ba2e8
	s_add_u32 s26, s29, s26
	s_addc_u32 s27, s28, s27
	s_ashr_i32 s28, s31, 31
	s_mul_i32 s29, s28, 0x2e8ba2e8
	s_mul_hi_u32 s31, s28, 0xba2e8ba3
	s_add_i32 s29, s31, s29
	s_mul_i32 s28, s28, 0xba2e8ba3
	s_add_i32 s29, s29, s28
	s_add_u32 s26, s26, s28
	s_addc_u32 s27, s27, s29
	s_ashr_i64 s[28:29], s[26:27], 10
	s_lshr_b32 s26, s27, 31
	s_add_u32 s26, s28, s26
	s_mulk_i32 s26, 0x1600
	s_sub_i32 s26, s30, s26
	s_sext_i32_i16 s27, s26
	s_bfe_u32 s27, s27, 0x3001c
	s_add_i32 s27, s26, s27
	s_waitcnt vmcnt(8)
	s_waitcnt lgkmcnt(0)
	s_barrier
; #define PG8_STAGE(bufoff, gbase, voff) do { _Pragma("unroll") for (int _i = 0; _i < 2; ++_i) \
;         __builtin_amdgcn_global_load_lds((const unsigned*)((const char*)(gbase) + (voff)[_i]), (LAS unsigned*)(lds + (bufoff) + ldsw + _i * 8192), 16, 0, 0); } while (0)
; #define PG8_LDA(dst, b, h) do { _Pragma("unroll") for (int m = 0; m < 4; ++m) _Pragma("unroll") for (int k = 0; k < 2; ++k) dst[m][k] = *(const LAS bf16x8*)(lds + PG8_SA(b, h) + aoff + m * 2048 + k * 1024); } while (0)
; #define PG8_LDB(dst, b, h) do { _Pragma("unroll") for (int n = 0; n < 2; ++n) _Pragma("unroll") for (int k = 0; k < 2; ++k) dst[n][k] = *(const LAS bf16x8*)(lds + PG8_SB(b, h) + boff + n * 2048 + k * 1024); } while (0)
; #define PG8_MMA(ai, bj, At, Bt) do { __builtin_amdgcn_s_setprio(1); _Pragma("unroll") for (int m = 0; m < 4; ++m) _Pragma("unroll") for (int n = 0; n < 2; ++n) _Pragma("unroll") for (int k = 0; k < 2; ++k) \
;         acc[ai][bj][m][n] = __builtin_amdgcn_mfma_f32_16x16x32_bf16(Bt[n][k], At[m][k], acc[ai][bj][m][n], 0, 0, 0); __builtin_amdgcn_s_setprio(0); } while (0)
; #define PG8_WAIT_V(n) asm volatile("s_waitcnt vmcnt(" #n ")" ::: "memory")
; #define PG8_WAIT_L(n) asm volatile("s_waitcnt lgkmcnt(" #n ")" ::: "memory")
; #define PG8_BAR __builtin_amdgcn_s_barrier()
; #define PG8_SCHED __builtin_amdgcn_sched_barrier(0)
;     DI bool next(int i, Unit& u) const {
;     ...
;         { const int q = nwg / NXCD, r = nwg % NXCD, xcd = wgid % NXCD, off = wgid / NXCD; wgid = (xcd < r ? xcd * (q + 1) : r * (q + 1) + (xcd - r) * q) + off; }
;         const int nig = WGM * nN, gid = wgid / nig, fm = gid * WGM, gsz = (nM - fm) < WGM ? (nM - fm) : WGM;
;         u.pm = fm + ((wgid % nig) % gsz); u.pn = (wgid % nig) / gsz; return true;
;     }
; template <class Epi>
; DI void gemm_phase(LAS unsigned char* lds, const int wid, const Gemm g, const Order& S, const Epi& E) {
;     ...
;             PG8_WAIT_V(8); PG8_WAIT_L(0); PG8_BAR; PG8_MMA(1, 0, At, B0); PG8_MMA(1, 1, At, B1); PG8_BAR; PG8_SCHED;
;             PG8_LDB(B0, 1, 0); PG8_LDB(B1, 1, 1); PG8_SCHED; PG8_LDA(At, 1, 0); PG8_STAGE(PG8_SA(0, 1), a2 + hstepA, voffA);
	s_setprio 1
	s_waitcnt lgkmcnt(0)
	v_mfma_f32_16x16x32_bf16 v[60:63], v[164:167], v[196:199], 0
	v_mfma_f32_16x16x32_bf16 v[56:59], v[172:175], v[196:199], 0
	v_mfma_f32_16x16x32_bf16 v[44:47], v[164:167], v[204:207], 0
	v_mfma_f32_16x16x32_bf16 v[40:43], v[172:175], v[204:207], 0
	v_mfma_f32_16x16x32_bf16 v[28:31], v[164:167], v[212:215], 0
	v_mfma_f32_16x16x32_bf16 v[24:27], v[172:175], v[212:215], 0
	v_mfma_f32_16x16x32_bf16 v[12:15], v[164:167], v[220:223], 0
	v_mfma_f32_16x16x32_bf16 v[8:11], v[172:175], v[220:223], 0
	v_mfma_f32_16x16x32_bf16 v[60:63], v[168:171], v[200:203], v[60:63]
	v_mfma_f32_16x16x32_bf16 v[56:59], v[176:179], v[200:203], v[56:59]
	v_mfma_f32_16x16x32_bf16 v[44:47], v[168:171], v[208:211], v[44:47]
	v_mfma_f32_16x16x32_bf16 v[40:43], v[176:179], v[208:211], v[40:43]
	v_mfma_f32_16x16x32_bf16 v[28:31], v[168:171], v[216:219], v[28:31]
	v_mfma_f32_16x16x32_bf16 v[24:27], v[176:179], v[216:219], v[24:27]
	v_mfma_f32_16x16x32_bf16 v[12:15], v[168:171], v[224:227], v[12:15]
	v_mfma_f32_16x16x32_bf16 v[8:11], v[176:179], v[224:227], v[8:11]
	s_setprio 0
	s_setprio 1
	v_mfma_f32_16x16x32_bf16 v[52:55], v[180:183], v[196:199], 0
	v_mfma_f32_16x16x32_bf16 v[48:51], v[188:191], v[196:199], 0
	v_mfma_f32_16x16x32_bf16 v[36:39], v[180:183], v[204:207], 0
	v_mfma_f32_16x16x32_bf16 v[32:35], v[188:191], v[204:207], 0
	v_mfma_f32_16x16x32_bf16 v[20:23], v[180:183], v[212:215], 0
	v_mfma_f32_16x16x32_bf16 v[16:19], v[188:191], v[212:215], 0
	v_mfma_f32_16x16x32_bf16 v[4:7], v[180:183], v[220:223], 0
	v_mfma_f32_16x16x32_bf16 v[0:3], v[188:191], v[220:223], 0
	v_mfma_f32_16x16x32_bf16 v[52:55], v[184:187], v[200:203], v[52:55]
	v_mfma_f32_16x16x32_bf16 v[48:51], v[192:195], v[200:203], v[48:51]
	v_mfma_f32_16x16x32_bf16 v[36:39], v[184:187], v[208:211], v[36:39]
	v_mfma_f32_16x16x32_bf16 v[32:35], v[192:195], v[208:211], v[32:35]
	v_mfma_f32_16x16x32_bf16 v[20:23], v[184:187], v[216:219], v[20:23]
	v_mfma_f32_16x16x32_bf16 v[16:19], v[192:195], v[216:219], v[16:19]
	v_mfma_f32_16x16x32_bf16 v[4:7], v[184:187], v[224:227], v[4:7]
	v_mfma_f32_16x16x32_bf16 v[0:3], v[192:195], v[224:227], v[0:3]
	s_setprio 0
	s_barrier
	s_add_i32 s61, 0, 0x18000
	v_add_u32_e32 v146, s61, v147
	s_add_i32 s62, 0, 0x1c000
	ds_read_b128 v[164:167], v146
	ds_read_b128 v[168:171], v146 offset:1024
	ds_read_b128 v[172:175], v146 offset:2048
	ds_read_b128 v[176:179], v146 offset:3072
	v_add_u32_e32 v146, s62, v147
	ds_read_b128 v[180:183], v146
	ds_read_b128 v[184:187], v146 offset:1024
	ds_read_b128 v[188:191], v146 offset:2048
	ds_read_b128 v[192:195], v146 offset:3072
	s_add_u32 s42, s42, 0x40000
	s_addc_u32 s43, s43, 0
	s_mov_b32 m0, s47
	v_lshl_add_u64 v[160:161], s[42:43], 0, v[134:135]
	ds_read_b128 v[196:199], v159 offset:32768
	ds_read_b128 v[200:203], v159 offset:33792
	ds_read_b128 v[204:207], v159 offset:34816
	ds_read_b128 v[208:211], v159 offset:35840
	ds_read_b128 v[212:215], v159 offset:36864
	ds_read_b128 v[216:219], v159 offset:37888
	ds_read_b128 v[220:223], v159 offset:38912
	ds_read_b128 v[224:227], v159 offset:39936
	global_load_lds_dwordx4 v[160:161], off
	v_lshl_add_u64 v[160:161], s[42:43], 0, v[130:131]
	s_mov_b32 m0, s48
	s_nop 0
	global_load_lds_dwordx4 v[160:161], off
	s_sext_i32_i16 s28, s27
	s_and_b32 s27, s27, 0xfff8
	s_sub_i32 s26, s26, s27
	s_ashr_i32 s28, s28, 3
	s_sext_i32_i16 s27, s26
	s_cmp_lt_i32 s27, 0
	s_cselect_b32 s27, s45, 0x2c0
	s_mul_i32 s26, s26, s27
	s_add_i32 s26, s26, s28
	s_sext_i32_i16 s27, s26
	s_mulk_i32 s27, 0xba3
	s_lshr_b32 s28, s27, 31
	s_ashr_i32 s27, s27, 19
	s_add_i32 s27, s27, s28
	s_lshl_b32 s28, s27, 3
	s_mulk_i32 s27, 0xb0
	s_sub_i32 s26, s26, s27
	s_sext_i32_i16 s27, s26
	s_bfe_u32 s27, s27, 0x3001c
	s_add_i32 s27, s26, s27
	s_sext_i32_i16 s29, s27
	s_and_b32 s27, s27, 0xfff8
	s_sub_i32 s26, s26, s27
	s_sext_i32_i16 s26, s26
	s_add_i32 s26, s28, s26
	s_ashr_i32 s28, s29, 3
	s_ashr_i32 s27, s26, 31
	s_lshl_b64 s[30:31], s[26:27], 19
	s_add_u32 s30, s6, s30
	s_addc_u32 s31, s7, s31
	s_and_b64 s[34:35], s[8:9], exec
	s_cselect_b32 s27, s31, s39
	s_cselect_b32 s56, s30, s38
	s_ashr_i32 s29, s28, 31
	s_lshl_b64 s[34:35], s[28:29], 19
	s_add_u32 s34, s21, s34
	s_addc_u32 s35, s44, s35
	s_and_b64 vcc, s[8:9], exec
	s_cselect_b32 s29, s35, s41
	s_cselect_b32 s57, s34, s40
	s_waitcnt vmcnt(8)
	s_waitcnt lgkmcnt(0)
	s_barrier
; #define PG8_STAGE(bufoff, gbase, voff) do { _Pragma("unroll") for (int _i = 0; _i < 2; ++_i) \
;         __builtin_amdgcn_global_load_lds((const unsigned*)((const char*)(gbase) + (voff)[_i]), (LAS unsigned*)(lds + (bufoff) + ldsw + _i * 8192), 16, 0, 0); } while (0)
; #define PG8_LDA(dst, b, h) do { _Pragma("unroll") for (int m = 0; m < 4; ++m) _Pragma("unroll") for (int k = 0; k < 2; ++k) dst[m][k] = *(const LAS bf16x8*)(lds + PG8_SA(b, h) + aoff + m * 2048 + k * 1024); } while (0)
; #define PG8_MMA(ai, bj, At, Bt) do { __builtin_amdgcn_s_setprio(1); _Pragma("unroll") for (int m = 0; m < 4; ++m) _Pragma("unroll") for (int n = 0; n < 2; ++n) _Pragma("unroll") for (int k = 0; k < 2; ++k) \
;         acc[ai][bj][m][n] = __builtin_amdgcn_mfma_f32_16x16x32_bf16(Bt[n][k], At[m][k], acc[ai][bj][m][n], 0, 0, 0); __builtin_amdgcn_s_setprio(0); } while (0)
; #define PG8_WAIT_V(n) asm volatile("s_waitcnt vmcnt(" #n ")" ::: "memory")
; #define PG8_WAIT_L(n) asm volatile("s_waitcnt lgkmcnt(" #n ")" ::: "memory")
; #define PG8_BAR __builtin_amdgcn_s_barrier()
; #define PG8_SCHED __builtin_amdgcn_sched_barrier(0)
; template <class Epi>
; DI void gemm_phase(LAS unsigned char* lds, const int wid, const Gemm g, const Order& S, const Epi& E) {
;     ...
;             PG8_WAIT_V(8); PG8_WAIT_L(0); PG8_BAR; PG8_MMA(0, 0, At, B0); PG8_MMA(0, 1, At, B1); PG8_BAR; PG8_SCHED;
;             PG8_LDA(At, 1, 1); PG8_STAGE(PG8_SB(1, 0), b3, voffB); PG8_STAGE(PG8_SB(1, 1), b3 + hstepB, voffB); PG8_STAGE(PG8_SA(1, 0), a3, voffA);
;             PG8_WAIT_V(8); PG8_WAIT_L(0); PG8_BAR; PG8_MMA(1, 0, At, B0); PG8_MMA(1, 1, At, B1); PG8_BAR; PG8_SCHED;
	s_setprio 1
	s_waitcnt lgkmcnt(0)
	v_mfma_f32_16x16x32_bf16 v[124:127], v[164:167], v[196:199], v[124:127]
	v_mfma_f32_16x16x32_bf16 v[120:123], v[172:175], v[196:199], v[120:123]
	v_mfma_f32_16x16x32_bf16 v[108:111], v[164:167], v[204:207], v[108:111]
	v_mfma_f32_16x16x32_bf16 v[104:107], v[172:175], v[204:207], v[104:107]
	v_mfma_f32_16x16x32_bf16 v[92:95], v[164:167], v[212:215], v[92:95]
	v_mfma_f32_16x16x32_bf16 v[88:91], v[172:175], v[212:215], v[88:91]
	v_mfma_f32_16x16x32_bf16 v[76:79], v[164:167], v[220:223], v[76:79]
	v_mfma_f32_16x16x32_bf16 v[72:75], v[172:175], v[220:223], v[72:75]
	v_mfma_f32_16x16x32_bf16 v[124:127], v[168:171], v[200:203], v[124:127]
	v_mfma_f32_16x16x32_bf16 v[120:123], v[176:179], v[200:203], v[120:123]
	v_mfma_f32_16x16x32_bf16 v[108:111], v[168:171], v[208:211], v[108:111]
	v_mfma_f32_16x16x32_bf16 v[104:107], v[176:179], v[208:211], v[104:107]
	v_mfma_f32_16x16x32_bf16 v[92:95], v[168:171], v[216:219], v[92:95]
	v_mfma_f32_16x16x32_bf16 v[88:91], v[176:179], v[216:219], v[88:91]
	v_mfma_f32_16x16x32_bf16 v[76:79], v[168:171], v[224:227], v[76:79]
	v_mfma_f32_16x16x32_bf16 v[72:75], v[176:179], v[224:227], v[72:75]
	s_setprio 0
	s_setprio 1
	v_mfma_f32_16x16x32_bf16 v[116:119], v[180:183], v[196:199], v[116:119]
	v_mfma_f32_16x16x32_bf16 v[112:115], v[188:191], v[196:199], v[112:115]
	v_mfma_f32_16x16x32_bf16 v[100:103], v[180:183], v[204:207], v[100:103]
	v_mfma_f32_16x16x32_bf16 v[96:99], v[188:191], v[204:207], v[96:99]
	v_mfma_f32_16x16x32_bf16 v[84:87], v[180:183], v[212:215], v[84:87]
	v_mfma_f32_16x16x32_bf16 v[80:83], v[188:191], v[212:215], v[80:83]
	v_mfma_f32_16x16x32_bf16 v[68:71], v[180:183], v[220:223], v[68:71]
	v_mfma_f32_16x16x32_bf16 v[64:67], v[188:191], v[220:223], v[64:67]
	v_mfma_f32_16x16x32_bf16 v[116:119], v[184:187], v[200:203], v[116:119]
	v_mfma_f32_16x16x32_bf16 v[112:115], v[192:195], v[200:203], v[112:115]
	v_mfma_f32_16x16x32_bf16 v[100:103], v[184:187], v[208:211], v[100:103]
	v_mfma_f32_16x16x32_bf16 v[96:99], v[192:195], v[208:211], v[96:99]
	v_mfma_f32_16x16x32_bf16 v[84:87], v[184:187], v[216:219], v[84:87]
	v_mfma_f32_16x16x32_bf16 v[80:83], v[192:195], v[216:219], v[80:83]
	v_mfma_f32_16x16x32_bf16 v[68:71], v[184:187], v[224:227], v[68:71]
	v_mfma_f32_16x16x32_bf16 v[64:67], v[192:195], v[224:227], v[64:67]
	s_setprio 0
	s_barrier
	s_add_i32 s42, s61, s94
	v_lshl_add_u64 v[144:145], v[144:145], 0, s[16:17]
	s_mov_b32 m0, s42
	ds_read_b128 v[196:199], v159 offset:49152
	ds_read_b128 v[200:203], v159 offset:50176
	ds_read_b128 v[204:207], v159 offset:51200
	ds_read_b128 v[208:211], v159 offset:52224
	ds_read_b128 v[212:215], v159 offset:53248
	ds_read_b128 v[216:219], v159 offset:54272
	ds_read_b128 v[220:223], v159 offset:55296
	ds_read_b128 v[224:227], v159 offset:56320
	global_load_lds_dwordx4 v[144:145], off
	s_add_i32 m0, s42, 0x2000
	s_add_u32 s40, s40, 0x40080
	v_lshl_add_u64 v[144:145], v[148:149], 0, s[16:17]
	s_addc_u32 s41, s41, 0
	s_add_i32 s42, s62, s94
	global_load_lds_dwordx4 v[144:145], off
	v_lshl_add_u64 v[144:145], s[40:41], 0, v[132:133]
	s_mov_b32 m0, s42
	s_nop 0
	global_load_lds_dwordx4 v[144:145], off
	v_lshl_add_u64 v[144:145], s[40:41], 0, v[128:129]
	s_add_i32 m0, s42, 0x2000
	s_nop 0
	global_load_lds_dwordx4 v[144:145], off
	v_lshl_add_u64 v[144:145], v[152:153], 0, s[16:17]
	s_mov_b32 m0, s51
	s_nop 0
	global_load_lds_dwordx4 v[144:145], off
	v_lshl_add_u64 v[144:145], v[156:157], 0, s[16:17]
	s_mov_b32 m0, s52
	s_nop 0
	global_load_lds_dwordx4 v[144:145], off
	s_waitcnt vmcnt(8)
	s_waitcnt lgkmcnt(0)
	s_barrier
	s_setprio 1
	s_waitcnt lgkmcnt(0)
	v_mfma_f32_16x16x32_bf16 v[60:63], v[164:167], v[196:199], v[60:63]
	v_mfma_f32_16x16x32_bf16 v[56:59], v[172:175], v[196:199], v[56:59]
	v_mfma_f32_16x16x32_bf16 v[44:47], v[164:167], v[204:207], v[44:47]
	v_mfma_f32_16x16x32_bf16 v[40:43], v[172:175], v[204:207], v[40:43]
	v_mfma_f32_16x16x32_bf16 v[28:31], v[164:167], v[212:215], v[28:31]
	v_mfma_f32_16x16x32_bf16 v[24:27], v[172:175], v[212:215], v[24:27]
	v_mfma_f32_16x16x32_bf16 v[12:15], v[164:167], v[220:223], v[12:15]
	v_mfma_f32_16x16x32_bf16 v[8:11], v[172:175], v[220:223], v[8:11]
	v_mfma_f32_16x16x32_bf16 v[60:63], v[168:171], v[200:203], v[60:63]
	v_mfma_f32_16x16x32_bf16 v[56:59], v[176:179], v[200:203], v[56:59]
	v_mfma_f32_16x16x32_bf16 v[44:47], v[168:171], v[208:211], v[44:47]
	v_mfma_f32_16x16x32_bf16 v[40:43], v[176:179], v[208:211], v[40:43]
	v_mfma_f32_16x16x32_bf16 v[28:31], v[168:171], v[216:219], v[28:31]
	v_mfma_f32_16x16x32_bf16 v[24:27], v[176:179], v[216:219], v[24:27]
	v_mfma_f32_16x16x32_bf16 v[12:15], v[168:171], v[224:227], v[12:15]
	v_mfma_f32_16x16x32_bf16 v[8:11], v[176:179], v[224:227], v[8:11]
	s_setprio 0
	s_setprio 1
	v_mfma_f32_16x16x32_bf16 v[52:55], v[180:183], v[196:199], v[52:55]
	v_mfma_f32_16x16x32_bf16 v[48:51], v[188:191], v[196:199], v[48:51]
	v_mfma_f32_16x16x32_bf16 v[36:39], v[180:183], v[204:207], v[36:39]
	v_mfma_f32_16x16x32_bf16 v[32:35], v[188:191], v[204:207], v[32:35]
	v_mfma_f32_16x16x32_bf16 v[20:23], v[180:183], v[212:215], v[20:23]
	v_mfma_f32_16x16x32_bf16 v[16:19], v[188:191], v[212:215], v[16:19]
	v_mfma_f32_16x16x32_bf16 v[4:7], v[180:183], v[220:223], v[4:7]
	v_mfma_f32_16x16x32_bf16 v[0:3], v[188:191], v[220:223], v[0:3]
	v_mfma_f32_16x16x32_bf16 v[52:55], v[184:187], v[200:203], v[52:55]
	v_mfma_f32_16x16x32_bf16 v[48:51], v[192:195], v[200:203], v[48:51]
	v_mfma_f32_16x16x32_bf16 v[36:39], v[184:187], v[208:211], v[36:39]
	v_mfma_f32_16x16x32_bf16 v[32:35], v[192:195], v[208:211], v[32:35]
	v_mfma_f32_16x16x32_bf16 v[20:23], v[184:187], v[216:219], v[20:23]
	v_mfma_f32_16x16x32_bf16 v[16:19], v[192:195], v[216:219], v[16:19]
	v_mfma_f32_16x16x32_bf16 v[4:7], v[184:187], v[224:227], v[4:7]
	v_mfma_f32_16x16x32_bf16 v[0:3], v[192:195], v[224:227], v[0:3]
	s_setprio 0
	s_barrier
	s_add_i32 s60, s60, 2
	s_add_u32 s38, s38, 0x100
	s_addc_u32 s39, s39, 0
	s_add_u32 s58, s58, 0x100
	s_addc_u32 s59, s59, 0
	s_cmp_gt_u32 s60, 13
	s_cbranch_scc0 .LBB0_1336
	s_branch .Lpeel_exit_9
